# v64 + ph0 tr_item LDS-read hoist + attention staging: K/V, LUT, sink and Q loads issued back to back (one exposed latency)
# baseline (speedup 1.0000x reference)
.Lattn_body:
	ds_read_b128 v[48:51], v153
	ds_read_b128 v[52:55], v153 offset:64
	s_cmp_eq_u32 s20, 0
	s_cselect_b64 vcc, -1, 0
	s_mov_b32 s7, 0xf149f2ca
	s_mov_b32 s6, 0x3fb8aa3b
	v_lshl_add_u64 v[134:135], v[130:131], 0, s[0:1]
	s_add_i32 s20, s11, 1
	v_readlane_b32 s36, v252, 10
	v_readlane_b32 s37, v252, 11
	s_waitcnt vmcnt(15) lgkmcnt(1)
	v_mfma_f32_16x16x32_bf16 v[56:59], v[48:51], v[84:87], 0
	v_mul_f32_e32 v133, 0x3fb8aa3b, v162
	s_waitcnt vmcnt(13)
	v_mfma_f32_16x16x32_bf16 v[48:51], v[48:51], v[92:95], 0
	s_waitcnt lgkmcnt(0)
	v_mfma_f32_16x16x32_bf16 v[100:103], v[52:55], v[88:91], v[56:59]
	s_waitcnt vmcnt(12)
	v_mfma_f32_16x16x32_bf16 v[48:51], v[52:55], v[96:99], v[48:51]
	ds_read_b128 v[52:55], v153 offset:2304
	ds_read_b128 v[56:59], v153 offset:2368
	s_waitcnt lgkmcnt(1)
	v_mfma_f32_16x16x32_bf16 v[60:63], v[52:55], v[84:87], 0
	v_mfma_f32_16x16x32_bf16 v[52:55], v[52:55], v[92:95], 0
	s_waitcnt lgkmcnt(0)
	v_mfma_f32_16x16x32_bf16 v[104:107], v[56:59], v[88:91], v[60:63]
	v_mfma_f32_16x16x32_bf16 v[52:55], v[56:59], v[96:99], v[52:55]
	ds_read_b128 v[56:59], v153 offset:4608
	s_nop 2
	ds_read_b128 v[60:63], v153 offset:4672
	s_waitcnt lgkmcnt(1)
	v_mfma_f32_16x16x32_bf16 v[64:67], v[56:59], v[84:87], 0
	v_mfma_f32_16x16x32_bf16 v[56:59], v[56:59], v[92:95], 0
	s_waitcnt lgkmcnt(0)
	v_mfma_f32_16x16x32_bf16 v[108:111], v[60:63], v[88:91], v[64:67]
	v_mfma_f32_16x16x32_bf16 v[56:59], v[60:63], v[96:99], v[56:59]
	ds_read_b128 v[60:63], v153 offset:6912
	s_nop 2
	ds_read_b128 v[64:67], v153 offset:6976
	s_waitcnt lgkmcnt(1)
	v_mfma_f32_16x16x32_bf16 v[68:71], v[60:63], v[84:87], 0
	v_mfma_f32_16x16x32_bf16 v[60:63], v[60:63], v[92:95], 0
	s_waitcnt lgkmcnt(0)
	v_mfma_f32_16x16x32_bf16 v[112:115], v[64:67], v[88:91], v[68:71]
	v_mfma_f32_16x16x32_bf16 v[60:63], v[64:67], v[96:99], v[60:63]
	ds_read_b128 v[64:67], v153 offset:9216
	s_nop 2
	ds_read_b128 v[68:71], v153 offset:9280
	s_waitcnt lgkmcnt(1)
	v_mfma_f32_16x16x32_bf16 v[72:75], v[64:67], v[84:87], 0
	v_mfma_f32_16x16x32_bf16 v[64:67], v[64:67], v[92:95], 0
	s_waitcnt lgkmcnt(0)
	v_mfma_f32_16x16x32_bf16 v[116:119], v[68:71], v[88:91], v[72:75]
	v_mfma_f32_16x16x32_bf16 v[64:67], v[68:71], v[96:99], v[64:67]
	ds_read_b128 v[68:71], v153 offset:11520
	s_nop 2
	ds_read_b128 v[72:75], v153 offset:11584
	s_waitcnt lgkmcnt(1)
	v_mfma_f32_16x16x32_bf16 v[76:79], v[68:71], v[84:87], 0
	v_mfma_f32_16x16x32_bf16 v[68:71], v[68:71], v[92:95], 0
	s_waitcnt lgkmcnt(0)
	v_mfma_f32_16x16x32_bf16 v[120:123], v[72:75], v[88:91], v[76:79]
	v_mfma_f32_16x16x32_bf16 v[68:71], v[72:75], v[96:99], v[68:71]
	ds_read_b128 v[72:75], v153 offset:13824
	s_nop 2
	ds_read_b128 v[76:79], v153 offset:13888
	s_waitcnt lgkmcnt(1)
	v_mfma_f32_16x16x32_bf16 v[80:83], v[72:75], v[84:87], 0
	v_mfma_f32_16x16x32_bf16 v[72:75], v[72:75], v[92:95], 0
	s_waitcnt lgkmcnt(0)
	v_mfma_f32_16x16x32_bf16 v[124:127], v[76:79], v[88:91], v[80:83]
	v_mfma_f32_16x16x32_bf16 v[72:75], v[76:79], v[96:99], v[72:75]
	ds_read_b128 v[76:79], v153 offset:16128
	s_nop 2
	ds_read_b128 v[80:83], v153 offset:16192
	s_waitcnt lgkmcnt(1)
	v_mfma_f32_16x16x32_bf16 v[164:167], v[76:79], v[84:87], 0
	v_mfma_f32_16x16x32_bf16 v[76:79], v[76:79], v[92:95], 0
	s_waitcnt lgkmcnt(0)
	v_mfma_f32_16x16x32_bf16 v[164:167], v[80:83], v[88:91], v[164:167]
	v_mfma_f32_16x16x32_bf16 v[76:79], v[80:83], v[96:99], v[76:79]
	ds_read_b128 v[80:83], v153 offset:18432
	ds_read_b128 v[168:171], v153 offset:18496
	s_waitcnt lgkmcnt(1)
	v_mfma_f32_16x16x32_bf16 v[172:175], v[80:83], v[84:87], 0
	v_mfma_f32_16x16x32_bf16 v[80:83], v[80:83], v[92:95], 0
	s_waitcnt lgkmcnt(0)
	v_mfma_f32_16x16x32_bf16 v[210:213], v[168:171], v[88:91], v[172:175]
	v_mfma_f32_16x16x32_bf16 v[80:83], v[168:171], v[96:99], v[80:83]
	ds_read_b128 v[168:171], v153 offset:20736
	s_nop 2
	ds_read_b128 v[172:175], v153 offset:20800
	s_waitcnt lgkmcnt(1)
	v_mfma_f32_16x16x32_bf16 v[84:87], v[168:171], v[84:87], 0
	s_waitcnt lgkmcnt(0)
	v_mfma_f32_16x16x32_bf16 v[214:217], v[172:175], v[88:91], v[84:87]
	v_mfma_f32_16x16x32_bf16 v[84:87], v[168:171], v[92:95], 0
	v_mov_b32_e32 v92, 0xf149f2ca
	v_cndmask_b32_e32 v92, 0, v92, vcc
	v_mfma_f32_16x16x32_bf16 v[84:87], v[172:175], v[96:99], v[84:87]
	ds_read2_b32 v[94:95], v139 offset0:159 offset1:160
	ds_read2_b32 v[96:97], v139 offset0:157 offset1:158
	ds_read2_b32 v[98:99], v139 offset0:143 offset1:144
	ds_read2_b32 v[176:177], v139 offset0:141 offset1:142
	ds_read2_b32 v[178:179], v139 offset0:127 offset1:128
	ds_read2_b32 v[180:181], v139 offset0:125 offset1:126
	ds_read2_b32 v[182:183], v139 offset0:111 offset1:112
	ds_read2_b32 v[184:185], v139 offset0:109 offset1:110
	ds_read2_b32 v[186:187], v139 offset0:95 offset1:96
	ds_read2_b32 v[188:189], v139 offset0:93 offset1:94
	ds_read2_b32 v[190:191], v139 offset0:79 offset1:80
	ds_read2_b32 v[192:193], v139 offset0:77 offset1:78
	ds_read2_b32 v[194:195], v139 offset0:63 offset1:64
	ds_read2_b32 v[196:197], v139 offset0:61 offset1:62
	ds_read2_b32 v[90:91], v139 offset0:47 offset1:48
	ds_read2_b32 v[88:89], v139 offset0:45 offset1:46
	ds_read2_b32 v[198:199], v139 offset0:31 offset1:32
	ds_read2_b32 v[218:219], v139 offset0:29 offset1:30
	ds_read2_b32 v[220:221], v139 offset0:15 offset1:16
	ds_read2_b32 v[222:223], v139 offset0:13 offset1:14
	s_waitcnt lgkmcnt(14)
	v_add_f32_e32 v169, v92, v95
	v_add_f32_e32 v170, v92, v94
	v_add_f32_e32 v93, v100, v169
	v_add_f32_e32 v94, v101, v170
	v_add_f32_e32 v171, v92, v97
	v_add_f32_e32 v172, v92, v96
	v_max3_f32 v95, v93, s7, v94
	v_add_f32_e32 v97, v102, v171
	v_add_f32_e32 v96, v103, v172
	v_add_f32_e32 v173, v92, v99
	v_add_f32_e32 v174, v92, v98
	v_max3_f32 v95, v95, v97, v96
	v_add_f32_e32 v99, v104, v173
	v_add_f32_e32 v98, v105, v174
	v_add_f32_e32 v175, v92, v177
	v_add_f32_e32 v176, v92, v176
	v_max3_f32 v95, v95, v99, v98
	v_add_f32_e32 v100, v106, v175
	v_add_f32_e32 v101, v107, v176
	v_add_f32_e32 v177, v92, v179
	v_add_f32_e32 v178, v92, v178
	v_max3_f32 v95, v95, v100, v101
	v_add_f32_e32 v102, v108, v177
	v_add_f32_e32 v103, v109, v178
	v_add_f32_e32 v179, v92, v181
	v_add_f32_e32 v180, v92, v180
	v_max3_f32 v95, v95, v102, v103
	v_add_f32_e32 v104, v110, v179
	v_add_f32_e32 v105, v111, v180
	s_waitcnt lgkmcnt(13)
	v_add_f32_e32 v181, v92, v183
	v_add_f32_e32 v182, v92, v182
	v_max3_f32 v95, v95, v104, v105
	v_add_f32_e32 v106, v112, v181
	v_add_f32_e32 v107, v113, v182
	s_waitcnt lgkmcnt(12)
	v_add_f32_e32 v183, v92, v185
	v_add_f32_e32 v184, v92, v184
	v_max3_f32 v95, v95, v106, v107
	v_add_f32_e32 v108, v114, v183
	v_add_f32_e32 v109, v115, v184
	s_waitcnt lgkmcnt(11)
	v_add_f32_e32 v185, v92, v187
	v_add_f32_e32 v186, v92, v186
	v_max3_f32 v95, v95, v108, v109
	v_add_f32_e32 v110, v116, v185
	v_add_f32_e32 v111, v117, v186
	s_waitcnt lgkmcnt(10)
	v_add_f32_e32 v187, v92, v189
	v_add_f32_e32 v188, v92, v188
	v_max3_f32 v95, v95, v110, v111
	v_add_f32_e32 v112, v118, v187
	v_add_f32_e32 v113, v119, v188
	s_waitcnt lgkmcnt(9)
	v_add_f32_e32 v189, v92, v191
	v_add_f32_e32 v190, v92, v190
	v_max3_f32 v95, v95, v112, v113
	v_add_f32_e32 v114, v120, v189
	v_add_f32_e32 v115, v121, v190
	s_waitcnt lgkmcnt(8)
	v_add_f32_e32 v191, v92, v193
	v_add_f32_e32 v192, v92, v192
	v_max3_f32 v95, v95, v114, v115
	v_add_f32_e32 v116, v122, v191
	v_add_f32_e32 v117, v123, v192
	s_waitcnt lgkmcnt(7)
	v_add_f32_e32 v193, v92, v195
	v_add_f32_e32 v194, v92, v194
	s_waitcnt lgkmcnt(5)
	v_add_f32_e32 v118, v92, v91
	v_max3_f32 v95, v95, v116, v117
	v_add_f32_e32 v224, v124, v193
	v_add_f32_e32 v225, v125, v194
	v_add_f32_e32 v195, v92, v197
	v_add_f32_e32 v196, v92, v196
	v_add_f32_e32 v228, v164, v118
	v_add_f32_e32 v118, v92, v90
	v_max3_f32 v95, v95, v224, v225
	v_add_f32_e32 v226, v126, v195
	v_add_f32_e32 v227, v127, v196
	v_add_f32_e32 v229, v165, v118
	s_waitcnt lgkmcnt(4)
	v_add_f32_e32 v118, v92, v89
	v_max3_f32 v95, v95, v226, v227
	v_add_f32_e32 v230, v166, v118
	v_add_f32_e32 v118, v92, v88
	v_max3_f32 v95, v95, v228, v229
	v_add_f32_e32 v231, v167, v118
	s_waitcnt lgkmcnt(3)
	v_add_f32_e32 v197, 0, v199
	v_add_f32_e32 v198, 0, v198
	s_waitcnt lgkmcnt(1)
	v_add_f32_e32 v118, 0, v221
	v_max3_f32 v95, v95, v230, v231
	v_add_f32_e32 v232, v210, v197
	v_add_f32_e32 v211, v211, v198
	v_add_f32_e32 v199, 0, v219
	v_add_f32_e32 v210, 0, v218
	v_add_f32_e32 v214, v214, v118
	v_add_f32_e32 v118, 0, v220
	v_max3_f32 v95, v95, v232, v211
	v_add_f32_e32 v212, v212, v199
	v_add_f32_e32 v213, v213, v210
	v_add_f32_e32 v215, v215, v118
	s_waitcnt lgkmcnt(0)
	v_add_f32_e32 v118, 0, v223
	v_max3_f32 v95, v95, v212, v213
	v_add_f32_e32 v216, v216, v118
	v_add_f32_e32 v118, 0, v222
	v_max3_f32 v95, v95, v214, v215
	v_add_f32_e32 v217, v217, v118
	v_max3_f32 v95, v95, v216, v217
	ds_bpermute_b32 v118, v140, v95
	v_add_f32_e32 v52, v52, v169
	v_add_f32_e32 v53, v53, v170
	v_add_f32_e32 v54, v54, v171
	v_add_f32_e32 v55, v55, v172
	s_waitcnt lgkmcnt(0)
	v_max_f32_e32 v118, v118, v118
	v_max_f32_e32 v95, v95, v118
	ds_bpermute_b32 v118, v141, v95
	v_add_f32_e32 v56, v56, v173
	v_add_f32_e32 v57, v57, v174
	v_add_f32_e32 v58, v58, v175
	v_add_f32_e32 v59, v59, v176
	s_waitcnt lgkmcnt(0)
	v_max3_f32 v218, v95, v118, v133
	v_sub_f32_e32 v93, v93, v218
	v_exp_f32_e32 v126, v93
	v_sub_f32_e32 v94, v94, v218
	v_exp_f32_e32 v127, v94
	v_sub_f32_e32 v94, v97, v218
	v_exp_f32_e32 v163, v94
	v_sub_f32_e32 v94, v96, v218
	v_exp_f32_e32 v164, v94
	v_sub_f32_e32 v94, v99, v218
	v_add_f32_e32 v93, 0, v126
	v_exp_f32_e32 v165, v94
	v_sub_f32_e32 v94, v98, v218
	v_add_f32_e32 v93, v127, v93
	v_exp_f32_e32 v166, v94
	v_sub_f32_e32 v94, v100, v218
	v_add_f32_e32 v93, v163, v93
	v_exp_f32_e32 v167, v94
	v_sub_f32_e32 v94, v101, v218
	v_add_f32_e32 v93, v164, v93
	v_exp_f32_e32 v168, v94
	v_sub_f32_e32 v94, v102, v218
	v_add_f32_e32 v93, v165, v93
	v_exp_f32_e32 v118, v94
	v_sub_f32_e32 v94, v103, v218
	v_add_f32_e32 v93, v166, v93
	v_exp_f32_e32 v119, v94
	v_sub_f32_e32 v94, v104, v218
	v_add_f32_e32 v93, v167, v93
	v_exp_f32_e32 v120, v94
	v_sub_f32_e32 v94, v105, v218
	v_add_f32_e32 v93, v168, v93
	v_exp_f32_e32 v121, v94
	v_sub_f32_e32 v94, v106, v218
	v_add_f32_e32 v93, v118, v93
	v_exp_f32_e32 v122, v94
	v_sub_f32_e32 v94, v107, v218
	v_add_f32_e32 v93, v119, v93
	v_exp_f32_e32 v123, v94
	v_sub_f32_e32 v94, v108, v218
	v_add_f32_e32 v93, v120, v93
	v_exp_f32_e32 v124, v94
	v_sub_f32_e32 v94, v109, v218
	v_add_f32_e32 v93, v121, v93
	v_exp_f32_e32 v125, v94
	v_sub_f32_e32 v94, v110, v218
	v_add_f32_e32 v93, v122, v93
	v_exp_f32_e32 v110, v94
	v_sub_f32_e32 v94, v111, v218
	v_add_f32_e32 v93, v123, v93
	v_exp_f32_e32 v111, v94
	v_sub_f32_e32 v94, v112, v218
	v_add_f32_e32 v93, v124, v93
	v_exp_f32_e32 v112, v94
	v_sub_f32_e32 v94, v113, v218
	v_add_f32_e32 v93, v125, v93
	v_exp_f32_e32 v113, v94
	v_sub_f32_e32 v94, v114, v218
	v_add_f32_e32 v93, v110, v93
	v_exp_f32_e32 v114, v94
	v_sub_f32_e32 v94, v115, v218
	v_add_f32_e32 v93, v111, v93
	v_exp_f32_e32 v115, v94
	v_sub_f32_e32 v94, v116, v218
	v_add_f32_e32 v93, v112, v93
	v_exp_f32_e32 v116, v94
	v_sub_f32_e32 v94, v117, v218
	v_add_f32_e32 v93, v113, v93
	v_exp_f32_e32 v117, v94
	v_sub_f32_e32 v94, v224, v218
	v_add_f32_e32 v93, v114, v93
	v_exp_f32_e32 v102, v94
	v_sub_f32_e32 v94, v225, v218
	v_add_f32_e32 v93, v115, v93
	v_exp_f32_e32 v103, v94
	v_sub_f32_e32 v94, v226, v218
	v_add_f32_e32 v93, v116, v93
	v_exp_f32_e32 v104, v94
	v_sub_f32_e32 v94, v227, v218
	v_add_f32_e32 v93, v117, v93
	v_exp_f32_e32 v105, v94
	v_sub_f32_e32 v94, v228, v218
	v_add_f32_e32 v93, v102, v93
	v_exp_f32_e32 v106, v94
	v_sub_f32_e32 v94, v229, v218
	v_add_f32_e32 v93, v103, v93
	v_exp_f32_e32 v107, v94
	v_sub_f32_e32 v94, v230, v218
	v_add_f32_e32 v93, v104, v93
	v_exp_f32_e32 v108, v94
	v_sub_f32_e32 v94, v231, v218
	v_add_f32_e32 v93, v105, v93
	v_exp_f32_e32 v109, v94
	v_sub_f32_e32 v94, v232, v218
	v_add_f32_e32 v93, v106, v93
	v_exp_f32_e32 v94, v94
	v_sub_f32_e32 v95, v211, v218
	v_add_f32_e32 v93, v107, v93
	v_exp_f32_e32 v95, v95
	v_sub_f32_e32 v96, v212, v218
	v_add_f32_e32 v93, v108, v93
	v_exp_f32_e32 v96, v96
	v_sub_f32_e32 v97, v213, v218
	v_add_f32_e32 v93, v109, v93
	v_exp_f32_e32 v97, v97
	v_sub_f32_e32 v98, v214, v218
	v_add_f32_e32 v93, v94, v93
	v_exp_f32_e32 v98, v98
	v_sub_f32_e32 v99, v215, v218
	v_add_f32_e32 v93, v95, v93
	v_exp_f32_e32 v99, v99
	v_sub_f32_e32 v100, v216, v218
	v_add_f32_e32 v93, v96, v93
	v_exp_f32_e32 v100, v100
	v_sub_f32_e32 v101, v217, v218
	v_add_f32_e32 v93, v97, v93
	v_exp_f32_e32 v101, v101
	v_add_f32_e32 v93, v98, v93
	v_add_f32_e32 v93, v99, v93
	v_add_f32_e32 v93, v100, v93
	v_add_f32_e32 v93, v101, v93
	ds_bpermute_b32 v211, v140, v93
	v_add_f32_e32 v60, v60, v177
	v_add_f32_e32 v61, v61, v178
	v_add_f32_e32 v62, v62, v179
	v_add_f32_e32 v63, v63, v180
	s_waitcnt lgkmcnt(0)
	v_add_f32_e32 v93, v93, v211
	ds_bpermute_b32 v211, v141, v93
	v_add_f32_e32 v64, v64, v181
	v_add_f32_e32 v170, v65, v182
	v_add_f32_e32 v171, v67, v184
	v_add_f32_e32 v172, v68, v185
	s_waitcnt lgkmcnt(0)
	v_add_f32_e32 v93, v93, v211
	v_fma_f32 v211, v162, s6, -v218
	v_exp_f32_e32 v211, v211
	v_add_f32_e32 v173, v69, v186
	v_add_f32_e32 v174, v70, v187
	v_add_f32_e32 v175, v71, v188
	v_add_f32_e32 v93, v211, v93
	v_div_scale_f32 v211, s[0:1], v93, v93, 1.0
	v_rcp_f32_e32 v212, v211
	v_add_f32_e32 v176, v72, v189
	v_add_f32_e32 v177, v73, v190
	v_add_f32_e32 v178, v74, v191
	v_fma_f32 v213, -v211, v212, 1.0
	v_fmac_f32_e32 v212, v213, v212
	v_div_scale_f32 v213, vcc, 1.0, v93, 1.0
	v_mul_f32_e32 v214, v213, v212
	v_fma_f32 v215, -v211, v214, v213
	v_fmac_f32_e32 v214, v215, v212
	v_fma_f32 v211, -v211, v214, v213
	v_div_fmas_f32 v211, v211, v212, v214
	ds_read2_b32 v[212:213], v139 offset0:175 offset1:176
	ds_read2_b32 v[214:215], v139 offset0:173 offset1:174
	v_div_fixup_f32 v93, v211, v93, 1.0
	v_add_f32_e32 v179, v75, v192
	v_add_f32_e32 v180, v76, v193
	s_waitcnt lgkmcnt(1)
	v_add_f32_e32 v211, v92, v213
	v_add_f32_e32 v48, v48, v211
	v_add_f32_e32 v211, v92, v212
	s_waitcnt lgkmcnt(0)
	v_add_f32_e32 v212, v92, v215
	v_add_f32_e32 v49, v49, v211
	v_add_f32_e32 v50, v50, v212
	v_add_f32_e32 v212, v92, v214
	v_max3_f32 v211, v48, s7, v49
	v_add_f32_e32 v51, v51, v212
	v_max3_f32 v211, v211, v50, v51
	v_max3_f32 v169, v211, v52, v53
	v_max3_f32 v169, v169, v54, v55
	v_max3_f32 v169, v169, v56, v57
	v_max3_f32 v169, v169, v58, v59
	v_max3_f32 v169, v169, v60, v61
	v_max3_f32 v169, v169, v62, v63
	v_max3_f32 v65, v169, v64, v170
	v_add_f32_e32 v169, v66, v183
	v_max3_f32 v65, v65, v169, v171
	v_max3_f32 v65, v65, v172, v173
	v_max3_f32 v65, v65, v174, v175
	v_max3_f32 v65, v65, v176, v177
	v_add_f32_e32 v66, 0, v91
	v_max3_f32 v65, v65, v178, v179
	v_add_f32_e32 v181, v77, v194
	v_add_f32_e32 v91, v80, v66
	v_add_f32_e32 v66, 0, v90
	v_max3_f32 v65, v65, v180, v181
	v_add_f32_e32 v182, v78, v195
	v_add_f32_e32 v183, v79, v196
	v_add_f32_e32 v90, v81, v66
	v_add_f32_e32 v66, 0, v89
	v_max3_f32 v65, v65, v182, v183
	v_add_f32_e32 v89, v82, v66
	v_add_f32_e32 v66, 0, v88
	v_max3_f32 v65, v65, v91, v90
	v_add_f32_e32 v184, v83, v66
	v_max3_f32 v65, v65, v89, v184
	v_add_f32_e32 v185, v84, v197
	v_add_f32_e32 v186, v85, v198
	v_max3_f32 v65, v65, v185, v186
	v_add_f32_e32 v187, v86, v199
	v_add_f32_e32 v188, v87, v210
	v_max3_f32 v65, v65, v187, v188
	ds_bpermute_b32 v66, v140, v65
	s_waitcnt lgkmcnt(0)
	v_max_f32_e32 v66, v66, v66
	v_max_f32_e32 v65, v65, v66
	ds_bpermute_b32 v66, v141, v65
	s_waitcnt lgkmcnt(0)
	v_max3_f32 v189, v65, v66, v133
	v_sub_f32_e32 v48, v48, v189
	v_exp_f32_e32 v81, v48
	v_sub_f32_e32 v49, v49, v189
	v_exp_f32_e32 v82, v49
	v_sub_f32_e32 v49, v50, v189
	v_exp_f32_e32 v83, v49
	v_sub_f32_e32 v49, v51, v189
	v_exp_f32_e32 v84, v49
	v_sub_f32_e32 v49, v52, v189
	v_add_f32_e32 v48, 0, v81
	v_exp_f32_e32 v85, v49
	v_sub_f32_e32 v49, v53, v189
	v_add_f32_e32 v48, v82, v48
	v_exp_f32_e32 v86, v49
	v_sub_f32_e32 v49, v54, v189
	v_add_f32_e32 v48, v83, v48
	v_exp_f32_e32 v87, v49
	v_sub_f32_e32 v49, v55, v189
	v_add_f32_e32 v48, v84, v48
	v_exp_f32_e32 v88, v49
	v_sub_f32_e32 v49, v56, v189
	v_add_f32_e32 v48, v85, v48
	v_exp_f32_e32 v73, v49
	v_sub_f32_e32 v49, v57, v189
	v_add_f32_e32 v48, v86, v48
	v_exp_f32_e32 v74, v49
	v_sub_f32_e32 v49, v58, v189
	v_add_f32_e32 v48, v87, v48
	v_exp_f32_e32 v75, v49
	v_sub_f32_e32 v49, v59, v189
	v_add_f32_e32 v48, v88, v48
	v_exp_f32_e32 v76, v49
	v_sub_f32_e32 v49, v60, v189
	v_add_f32_e32 v48, v73, v48
	v_exp_f32_e32 v77, v49
	v_sub_f32_e32 v49, v61, v189
	v_add_f32_e32 v48, v74, v48
	v_exp_f32_e32 v78, v49
	v_sub_f32_e32 v49, v62, v189
	v_add_f32_e32 v48, v75, v48
	v_exp_f32_e32 v79, v49
	v_sub_f32_e32 v49, v63, v189
	v_add_f32_e32 v48, v76, v48
	v_exp_f32_e32 v80, v49
	v_sub_f32_e32 v49, v64, v189
	v_add_f32_e32 v48, v77, v48
	v_exp_f32_e32 v65, v49
	v_sub_f32_e32 v49, v170, v189
	v_add_f32_e32 v48, v78, v48
	v_exp_f32_e32 v66, v49
	v_sub_f32_e32 v49, v169, v189
	v_add_f32_e32 v48, v79, v48
	v_exp_f32_e32 v67, v49
	v_sub_f32_e32 v49, v171, v189
	v_add_f32_e32 v48, v80, v48
	v_exp_f32_e32 v68, v49
	v_sub_f32_e32 v49, v172, v189
	v_add_f32_e32 v48, v65, v48
	v_exp_f32_e32 v69, v49
	v_sub_f32_e32 v49, v173, v189
	v_add_f32_e32 v48, v66, v48
	v_exp_f32_e32 v70, v49
	v_sub_f32_e32 v49, v174, v189
	v_add_f32_e32 v48, v67, v48
	v_exp_f32_e32 v71, v49
	v_sub_f32_e32 v49, v175, v189
	v_add_f32_e32 v48, v68, v48
	v_exp_f32_e32 v72, v49
	v_sub_f32_e32 v49, v176, v189
	v_add_f32_e32 v48, v69, v48
	v_exp_f32_e32 v57, v49
	v_sub_f32_e32 v49, v177, v189
	v_add_f32_e32 v48, v70, v48
	v_exp_f32_e32 v58, v49
	v_sub_f32_e32 v49, v178, v189
	v_add_f32_e32 v48, v71, v48
	v_exp_f32_e32 v59, v49
	v_sub_f32_e32 v49, v179, v189
	v_add_f32_e32 v48, v72, v48
	v_exp_f32_e32 v60, v49
	v_sub_f32_e32 v49, v180, v189
	v_add_f32_e32 v48, v57, v48
	v_exp_f32_e32 v61, v49
	v_sub_f32_e32 v49, v181, v189
	v_add_f32_e32 v48, v58, v48
	v_exp_f32_e32 v62, v49
	v_sub_f32_e32 v49, v182, v189
	v_add_f32_e32 v48, v59, v48
	v_exp_f32_e32 v63, v49
	v_sub_f32_e32 v49, v183, v189
	v_add_f32_e32 v48, v60, v48
	v_exp_f32_e32 v64, v49
	v_sub_f32_e32 v49, v91, v189
	v_add_f32_e32 v48, v61, v48
	v_exp_f32_e32 v49, v49
	v_sub_f32_e32 v50, v90, v189
	v_add_f32_e32 v48, v62, v48
	v_exp_f32_e32 v50, v50
	v_sub_f32_e32 v51, v89, v189
	v_add_f32_e32 v48, v63, v48
	v_exp_f32_e32 v51, v51
	v_sub_f32_e32 v52, v184, v189
	v_add_f32_e32 v48, v64, v48
	v_exp_f32_e32 v52, v52
	v_sub_f32_e32 v53, v185, v189
	v_add_f32_e32 v48, v49, v48
	v_exp_f32_e32 v53, v53
	v_sub_f32_e32 v54, v186, v189
	v_add_f32_e32 v48, v50, v48
	v_exp_f32_e32 v54, v54
	v_sub_f32_e32 v55, v187, v189
	v_add_f32_e32 v48, v51, v48
	v_exp_f32_e32 v55, v55
	v_sub_f32_e32 v56, v188, v189
	v_add_f32_e32 v48, v52, v48
	v_exp_f32_e32 v56, v56
	v_add_f32_e32 v48, v53, v48
	v_add_f32_e32 v48, v54, v48
	v_add_f32_e32 v48, v55, v48
	v_add_f32_e32 v48, v56, v48
	ds_bpermute_b32 v89, v140, v48
	s_waitcnt lgkmcnt(0)
	v_add_f32_e32 v48, v48, v89
	ds_bpermute_b32 v89, v141, v48
	s_waitcnt lgkmcnt(0)
	v_add_f32_e32 v48, v48, v89
	v_fma_f32 v89, v162, s6, -v189
	v_exp_f32_e32 v89, v89
	s_nop 0
	v_add_f32_e32 v48, v89, v48
	v_div_scale_f32 v89, s[0:1], v48, v48, 1.0
	v_rcp_f32_e32 v90, v89
	s_nop 0
	v_fma_f32 v91, -v89, v90, 1.0
	v_fmac_f32_e32 v90, v91, v90
	v_div_scale_f32 v91, vcc, 1.0, v48, 1.0
	v_mul_f32_e32 v169, v91, v90
	v_fma_f32 v170, -v89, v169, v91
	v_fmac_f32_e32 v169, v170, v90
	v_fma_f32 v89, -v89, v169, v91
	v_div_fmas_f32 v89, v89, v90, v169
	v_div_fixup_f32 v48, v89, v48, 1.0
	v_cvt_pk_bf16_f32 v170, v126, v127
	v_cvt_pk_bf16_f32 v171, v163, v164
	v_cvt_pk_bf16_f32 v172, v165, v166
	v_cvt_pk_bf16_f32 v173, v167, v168
	v_cvt_pk_bf16_f32 v82, v81, v82
	v_cvt_pk_bf16_f32 v83, v83, v84
	v_cvt_pk_bf16_f32 v84, v85, v86
	v_cvt_pk_bf16_f32 v85, v87, v88
	ds_read_b128 v[86:89], v142 offset:36864
	ds_read_b128 v[174:177], v142 offset:45312
	ds_read_b128 v[182:185], v142 offset:53760
	ds_read_b128 v[190:193], v142 offset:62208
	v_cvt_pk_bf16_f32 v118, v118, v119
	v_cvt_pk_bf16_f32 v119, v120, v121
	v_cvt_pk_bf16_f32 v120, v122, v123
	v_cvt_pk_bf16_f32 v121, v124, v125
	v_cvt_pk_bf16_f32 v74, v73, v74
	v_cvt_pk_bf16_f32 v75, v75, v76
	v_cvt_pk_bf16_f32 v76, v77, v78
	v_cvt_pk_bf16_f32 v77, v79, v80
	ds_read_b128 v[78:81], v142 offset:36928
	s_waitcnt lgkmcnt(4)
	v_mfma_f32_16x16x32_bf16 v[164:167], v[86:89], v[170:173], 0
	v_mfma_f32_16x16x32_bf16 v[86:89], v[86:89], v[82:85], 0
	s_waitcnt lgkmcnt(0)
	v_mfma_f32_16x16x32_bf16 v[122:125], v[78:81], v[118:121], v[164:167]
	v_mfma_f32_16x16x32_bf16 v[78:81], v[78:81], v[74:77], v[86:89]
	s_nop 4
	ds_read_b128 v[86:89], v142 offset:45376
	v_mfma_f32_16x16x32_bf16 v[178:181], v[174:177], v[170:173], 0
	v_mfma_f32_16x16x32_bf16 v[174:177], v[174:177], v[82:85], 0
	v_mfma_f32_16x16x32_bf16 v[186:189], v[182:185], v[170:173], 0
	v_mfma_f32_16x16x32_bf16 v[168:171], v[190:193], v[170:173], 0
	s_waitcnt lgkmcnt(0)
	v_mfma_f32_16x16x32_bf16 v[164:167], v[86:89], v[118:121], v[178:181]
	v_mfma_f32_16x16x32_bf16 v[86:89], v[86:89], v[74:77], v[174:177]
	s_nop 2
	ds_read_b128 v[172:175], v142 offset:53824
	v_mfma_f32_16x16x32_bf16 v[182:185], v[182:185], v[82:85], 0
	s_waitcnt lgkmcnt(0)
	v_mfma_f32_16x16x32_bf16 v[176:179], v[172:175], v[118:121], v[186:189]
	v_mfma_f32_16x16x32_bf16 v[172:175], v[172:175], v[74:77], v[182:185]
	s_nop 4
	ds_read_b128 v[180:183], v142 offset:62272
	v_mfma_f32_16x16x32_bf16 v[82:85], v[190:193], v[82:85], 0
	s_waitcnt lgkmcnt(0)
	v_mfma_f32_16x16x32_bf16 v[74:77], v[180:183], v[74:77], v[82:85]
	v_cvt_pk_bf16_f32 v82, v110, v111
	v_cvt_pk_bf16_f32 v83, v112, v113
	v_cvt_pk_bf16_f32 v84, v114, v115
	v_cvt_pk_bf16_f32 v85, v116, v117
	v_cvt_pk_bf16_f32 v66, v65, v66
	v_cvt_pk_bf16_f32 v67, v67, v68
	v_cvt_pk_bf16_f32 v68, v69, v70
	v_cvt_pk_bf16_f32 v69, v71, v72
	ds_read_b128 v[70:73], v142 offset:36992
	s_waitcnt lgkmcnt(0)
	s_nop 3
	v_mfma_f32_16x16x32_bf16 v[110:113], v[70:73], v[82:85], v[122:125]
	v_mfma_f32_16x16x32_bf16 v[70:73], v[70:73], v[66:69], v[78:81]
	s_nop 2
	ds_read_b128 v[78:81], v142 offset:45440
	s_waitcnt lgkmcnt(0)
	v_mfma_f32_16x16x32_bf16 v[114:117], v[78:81], v[82:85], v[164:167]
	s_nop 2
	ds_read_b128 v[164:167], v142 offset:62336
	v_mfma_f32_16x16x32_bf16 v[78:81], v[78:81], v[66:69], v[86:89]
	s_nop 2
	ds_read_b128 v[86:89], v142 offset:53888
	s_waitcnt lgkmcnt(0)
	v_mfma_f32_16x16x32_bf16 v[122:125], v[86:89], v[82:85], v[176:179]
	v_mfma_f32_16x16x32_bf16 v[86:89], v[86:89], v[66:69], v[172:175]
	v_mfma_f32_16x16x32_bf16 v[66:69], v[164:167], v[66:69], v[74:77]
	v_cvt_pk_bf16_f32 v74, v102, v103
	v_cvt_pk_bf16_f32 v75, v104, v105
	v_cvt_pk_bf16_f32 v76, v106, v107
	v_cvt_pk_bf16_f32 v77, v108, v109
	v_cvt_pk_bf16_f32 v58, v57, v58
	v_cvt_pk_bf16_f32 v59, v59, v60
	v_cvt_pk_bf16_f32 v60, v61, v62
	v_cvt_pk_bf16_f32 v61, v63, v64
	ds_read_b128 v[62:65], v142 offset:37056
	s_waitcnt lgkmcnt(0)
	v_mfma_f32_16x16x32_bf16 v[102:105], v[62:65], v[74:77], v[110:113]
	v_mfma_f32_16x16x32_bf16 v[62:65], v[62:65], v[58:61], v[70:73]
	s_nop 2
	ds_read_b128 v[70:73], v142 offset:45504
	s_waitcnt lgkmcnt(0)
	v_mfma_f32_16x16x32_bf16 v[106:109], v[70:73], v[74:77], v[114:117]
	v_mfma_f32_16x16x32_bf16 v[70:73], v[70:73], v[58:61], v[78:81]
	s_nop 2
	ds_read_b128 v[78:81], v142 offset:53952
	s_waitcnt lgkmcnt(0)
	v_mfma_f32_16x16x32_bf16 v[110:113], v[78:81], v[74:77], v[122:125]
	v_mfma_f32_16x16x32_bf16 v[78:81], v[78:81], v[58:61], v[86:89]
	s_nop 2
	ds_read_b128 v[86:89], v142 offset:62400
	s_waitcnt lgkmcnt(0)
	v_mfma_f32_16x16x32_bf16 v[58:61], v[86:89], v[58:61], v[66:69]
	v_cvt_pk_bf16_f32 v66, v94, v95
	v_cvt_pk_bf16_f32 v67, v96, v97
	v_cvt_pk_bf16_f32 v68, v98, v99
	v_cvt_pk_bf16_f32 v69, v100, v101
	v_cvt_pk_bf16_f32 v50, v49, v50
	v_cvt_pk_bf16_f32 v51, v51, v52
	v_cvt_pk_bf16_f32 v52, v53, v54
	v_cvt_pk_bf16_f32 v53, v55, v56
	ds_read_b128 v[54:57], v142 offset:37120
	v_mfma_f32_16x16x32_bf16 v[118:121], v[180:183], v[118:121], v[168:171]
	v_mfma_f32_16x16x32_bf16 v[82:85], v[164:167], v[82:85], v[118:121]
	v_mfma_f32_16x16x32_bf16 v[74:77], v[86:89], v[74:77], v[82:85]
	s_waitcnt lgkmcnt(0)
	v_mfma_f32_16x16x32_bf16 v[82:85], v[54:57], v[66:69], v[102:105]
	v_mfma_f32_16x16x32_bf16 v[54:57], v[54:57], v[50:53], v[62:65]
	s_nop 2
	ds_read_b128 v[62:65], v142 offset:45568
	s_waitcnt lgkmcnt(0)
	v_mfma_f32_16x16x32_bf16 v[86:89], v[62:65], v[66:69], v[106:109]
	s_nop 0
	v_mul_f32_e32 v49, v93, v82
	v_mfma_f32_16x16x32_bf16 v[62:65], v[62:65], v[50:53], v[70:73]
	s_nop 2
	ds_read_b128 v[70:73], v142 offset:54016
	s_waitcnt lgkmcnt(0)
	v_mfma_f32_16x16x32_bf16 v[94:97], v[70:73], v[66:69], v[110:113]
	v_mfma_f32_16x16x32_bf16 v[70:73], v[70:73], v[50:53], v[78:81]
	s_nop 2
	ds_read_b128 v[78:81], v142 offset:62464
	s_waitcnt lgkmcnt(0)
	v_mfma_f32_16x16x32_bf16 v[50:53], v[78:81], v[50:53], v[58:61]
	s_nop 2
	v_mul_f32_e32 v60, v93, v83
	v_mul_f32_e32 v61, v93, v85
	v_lshl_add_u64 v[58:59], v[134:135], 0, v[136:137]
	v_cvt_pk_bf16_f32 v60, v49, v60
	v_mul_f32_e32 v49, v93, v84
	v_cvt_pk_bf16_f32 v61, v49, v61
	v_mfma_f32_16x16x32_bf16 v[66:69], v[78:81], v[66:69], v[74:77]
	global_store_dwordx2 v[58:59], v[60:61], off
	v_mul_f32_e32 v49, v93, v86
	v_mul_f32_e32 v60, v93, v87
	v_mul_f32_e32 v61, v93, v89
	v_cvt_pk_bf16_f32 v60, v49, v60
	v_mul_f32_e32 v49, v93, v88
	v_cvt_pk_bf16_f32 v61, v49, v61
	global_store_dwordx2 v[58:59], v[60:61], off offset:32
	v_mul_f32_e32 v49, v93, v94
	v_mul_f32_e32 v60, v93, v95
	v_mul_f32_e32 v61, v93, v97
	v_cvt_pk_bf16_f32 v60, v49, v60
	v_mul_f32_e32 v49, v93, v96
	v_cvt_pk_bf16_f32 v61, v49, v61
	global_store_dwordx2 v[58:59], v[60:61], off offset:64
	v_mul_f32_e32 v49, v93, v66
	v_mul_f32_e32 v60, v93, v67
	v_mul_f32_e32 v61, v93, v69
	v_cvt_pk_bf16_f32 v60, v49, v60
	v_mul_f32_e32 v49, v93, v68
	v_cvt_pk_bf16_f32 v61, v49, v61
	global_store_dwordx2 v[58:59], v[60:61], off offset:96
	v_or_b32_e32 v58, 16, v132
	v_ashrrev_i32_e32 v59, 31, v58
	v_lshlrev_b64 v[58:59], 12, v[58:59]
	v_mul_f32_e32 v49, v48, v54
	v_mul_f32_e32 v54, v48, v55
	v_lshl_add_u64 v[58:59], v[134:135], 0, v[58:59]
	v_cvt_pk_bf16_f32 v54, v49, v54
	v_mul_f32_e32 v49, v48, v56
	v_mul_f32_e32 v55, v48, v57
	v_cvt_pk_bf16_f32 v55, v49, v55
	global_store_dwordx2 v[58:59], v[54:55], off
	v_mul_f32_e32 v49, v48, v62
	v_mul_f32_e32 v54, v48, v63
	v_cvt_pk_bf16_f32 v54, v49, v54
	v_mul_f32_e32 v49, v48, v64
	v_mul_f32_e32 v55, v48, v65
	v_cvt_pk_bf16_f32 v55, v49, v55
	global_store_dwordx2 v[58:59], v[54:55], off offset:32
	v_mul_f32_e32 v49, v48, v70
	v_mul_f32_e32 v54, v48, v71
	v_cvt_pk_bf16_f32 v54, v49, v54
	v_mul_f32_e32 v49, v48, v72
	v_mul_f32_e32 v55, v48, v73
	v_cvt_pk_bf16_f32 v55, v49, v55
	v_mul_f32_e32 v49, v48, v50
	v_mul_f32_e32 v50, v48, v51
	global_store_dwordx2 v[58:59], v[54:55], off offset:64
	v_cvt_pk_bf16_f32 v50, v49, v50
	v_mul_f32_e32 v49, v48, v52
	v_mul_f32_e32 v48, v48, v53
	v_cvt_pk_bf16_f32 v51, v49, v48
	global_store_dwordx2 v[58:59], v[50:51], off offset:96
	ds_read_b128 v[48:51], v153 offset:4608
	ds_read_b128 v[52:55], v153 offset:4672
	s_waitcnt vmcnt(19) lgkmcnt(1)
	v_mfma_f32_16x16x32_bf16 v[56:59], v[48:51], v[36:39], 0
	s_waitcnt vmcnt(17)
	v_mfma_f32_16x16x32_bf16 v[48:51], v[48:51], v[40:43], 0
	s_waitcnt lgkmcnt(0)
	v_mfma_f32_16x16x32_bf16 v[84:87], v[52:55], v[32:35], v[56:59]
	s_waitcnt vmcnt(16)
	v_mfma_f32_16x16x32_bf16 v[48:51], v[52:55], v[44:47], v[48:51]
	ds_read_b128 v[52:55], v153 offset:6912
	s_nop 0
	ds_read_b128 v[56:59], v153 offset:6976
	s_waitcnt lgkmcnt(1)
	v_mfma_f32_16x16x32_bf16 v[60:63], v[52:55], v[36:39], 0
	v_mfma_f32_16x16x32_bf16 v[52:55], v[52:55], v[40:43], 0
	s_waitcnt lgkmcnt(0)
	v_mfma_f32_16x16x32_bf16 v[88:91], v[56:59], v[32:35], v[60:63]
	v_mfma_f32_16x16x32_bf16 v[52:55], v[56:59], v[44:47], v[52:55]
	ds_read_b128 v[56:59], v153 offset:9216
	s_nop 2
	ds_read_b128 v[60:63], v153 offset:9280
	s_waitcnt lgkmcnt(1)
	v_mfma_f32_16x16x32_bf16 v[64:67], v[56:59], v[36:39], 0
	v_mfma_f32_16x16x32_bf16 v[56:59], v[56:59], v[40:43], 0
	s_waitcnt lgkmcnt(0)
	v_mfma_f32_16x16x32_bf16 v[94:97], v[60:63], v[32:35], v[64:67]
	v_mfma_f32_16x16x32_bf16 v[56:59], v[60:63], v[44:47], v[56:59]
	ds_read_b128 v[60:63], v153 offset:11520
	s_nop 2
	ds_read_b128 v[64:67], v153 offset:11584
	s_waitcnt lgkmcnt(1)
	v_mfma_f32_16x16x32_bf16 v[68:71], v[60:63], v[36:39], 0
	v_mfma_f32_16x16x32_bf16 v[60:63], v[60:63], v[40:43], 0
	s_waitcnt lgkmcnt(0)
	v_mfma_f32_16x16x32_bf16 v[98:101], v[64:67], v[32:35], v[68:71]
	v_mfma_f32_16x16x32_bf16 v[60:63], v[64:67], v[44:47], v[60:63]
	ds_read_b128 v[64:67], v153 offset:13824
	s_nop 2
	ds_read_b128 v[68:71], v153 offset:13888
	s_waitcnt lgkmcnt(1)
	v_mfma_f32_16x16x32_bf16 v[72:75], v[64:67], v[36:39], 0
	v_mfma_f32_16x16x32_bf16 v[64:67], v[64:67], v[40:43], 0
	s_waitcnt lgkmcnt(0)
	v_mfma_f32_16x16x32_bf16 v[102:105], v[68:71], v[32:35], v[72:75]
	v_mfma_f32_16x16x32_bf16 v[64:67], v[68:71], v[44:47], v[64:67]
	ds_read_b128 v[68:71], v153 offset:16128
	s_nop 2
	ds_read_b128 v[72:75], v153 offset:16192
	s_waitcnt lgkmcnt(1)
	v_mfma_f32_16x16x32_bf16 v[76:79], v[68:71], v[36:39], 0
	v_mfma_f32_16x16x32_bf16 v[68:71], v[68:71], v[40:43], 0
	s_waitcnt lgkmcnt(0)
	v_mfma_f32_16x16x32_bf16 v[106:109], v[72:75], v[32:35], v[76:79]
	v_mfma_f32_16x16x32_bf16 v[68:71], v[72:75], v[44:47], v[68:71]
	ds_read_b128 v[72:75], v153 offset:18432
	s_nop 2
	ds_read_b128 v[76:79], v153 offset:18496
	s_waitcnt lgkmcnt(1)
	v_mfma_f32_16x16x32_bf16 v[80:83], v[72:75], v[36:39], 0
	v_mfma_f32_16x16x32_bf16 v[72:75], v[72:75], v[40:43], 0
	s_waitcnt lgkmcnt(0)
	v_mfma_f32_16x16x32_bf16 v[110:113], v[76:79], v[32:35], v[80:83]
	v_mfma_f32_16x16x32_bf16 v[72:75], v[76:79], v[44:47], v[72:75]
	ds_read_b128 v[76:79], v153 offset:20736
	s_nop 2
	ds_read_b128 v[80:83], v153 offset:20800
	s_waitcnt lgkmcnt(1)
	v_mfma_f32_16x16x32_bf16 v[114:117], v[76:79], v[36:39], 0
	v_mfma_f32_16x16x32_bf16 v[76:79], v[76:79], v[40:43], 0
	s_waitcnt lgkmcnt(0)
	v_mfma_f32_16x16x32_bf16 v[114:117], v[80:83], v[32:35], v[114:117]
	v_mfma_f32_16x16x32_bf16 v[76:79], v[80:83], v[44:47], v[76:79]
	ds_read_b128 v[80:83], v153 offset:23040
	ds_read_b128 v[118:121], v153 offset:23104
	s_waitcnt lgkmcnt(1)
	v_mfma_f32_16x16x32_bf16 v[122:125], v[80:83], v[36:39], 0
	v_mfma_f32_16x16x32_bf16 v[80:83], v[80:83], v[40:43], 0
	s_waitcnt lgkmcnt(0)
	v_mfma_f32_16x16x32_bf16 v[180:183], v[118:121], v[32:35], v[122:125]
	v_mfma_f32_16x16x32_bf16 v[80:83], v[118:121], v[44:47], v[80:83]
	ds_read_b128 v[118:121], v153 offset:25344
	s_nop 2
	ds_read_b128 v[122:125], v153 offset:25408
	s_waitcnt lgkmcnt(1)
	v_mfma_f32_16x16x32_bf16 v[36:39], v[118:121], v[36:39], 0
	s_waitcnt lgkmcnt(0)
	v_mfma_f32_16x16x32_bf16 v[184:187], v[122:125], v[32:35], v[36:39]
	v_mfma_f32_16x16x32_bf16 v[32:35], v[118:121], v[40:43], 0
	v_mfma_f32_16x16x32_bf16 v[32:35], v[122:125], v[44:47], v[32:35]
	ds_read2_b32 v[40:41], v139 offset0:159 offset1:160
	ds_read2_b32 v[42:43], v139 offset0:157 offset1:158
	ds_read2_b32 v[44:45], v139 offset0:143 offset1:144
	ds_read2_b32 v[46:47], v139 offset0:141 offset1:142
	ds_read2_b32 v[136:137], v139 offset0:127 offset1:128
	ds_read2_b32 v[164:165], v139 offset0:125 offset1:126
	ds_read2_b32 v[166:167], v139 offset0:111 offset1:112
	ds_read2_b32 v[168:169], v139 offset0:109 offset1:110
	ds_read2_b32 v[170:171], v139 offset0:95 offset1:96
	ds_read2_b32 v[172:173], v139 offset0:93 offset1:94
	ds_read2_b32 v[38:39], v139 offset0:79 offset1:80
	ds_read2_b32 v[36:37], v139 offset0:77 offset1:78
	ds_read2_b32 v[174:175], v139 offset0:63 offset1:64
	ds_read2_b32 v[176:177], v139 offset0:61 offset1:62
	ds_read2_b32 v[178:179], v139 offset0:47 offset1:48
	ds_read2_b32 v[188:189], v139 offset0:45 offset1:46
	ds_read2_b32 v[190:191], v139 offset0:31 offset1:32
	ds_read2_b32 v[192:193], v139 offset0:29 offset1:30
	ds_read2_b32 v[194:195], v139 offset0:15 offset1:16
	ds_read2_b32 v[196:197], v139 offset0:13 offset1:14
	s_waitcnt lgkmcnt(14)
	v_add_f32_e32 v118, v92, v41
	v_add_f32_e32 v119, v92, v40
	v_add_f32_e32 v41, v84, v118
	v_add_f32_e32 v40, v85, v119
	v_add_f32_e32 v120, v92, v43
	v_add_f32_e32 v121, v92, v42
	v_max3_f32 v84, v41, s7, v40
	v_add_f32_e32 v43, v86, v120
	v_add_f32_e32 v42, v87, v121
	v_add_f32_e32 v122, v92, v45
	v_add_f32_e32 v123, v92, v44
	v_max3_f32 v84, v84, v43, v42
	v_add_f32_e32 v45, v88, v122
	v_add_f32_e32 v44, v89, v123
	v_add_f32_e32 v124, v92, v47
	v_add_f32_e32 v125, v92, v46
	v_max3_f32 v84, v84, v45, v44
	v_add_f32_e32 v47, v90, v124
	v_add_f32_e32 v46, v91, v125
	v_add_f32_e32 v126, v92, v137
	v_add_f32_e32 v127, v92, v136
	v_max3_f32 v84, v84, v47, v46
	v_add_f32_e32 v85, v94, v126
	v_add_f32_e32 v86, v95, v127
	v_add_f32_e32 v136, v92, v165
	v_add_f32_e32 v137, v92, v164
	v_max3_f32 v84, v84, v85, v86
	v_add_f32_e32 v87, v96, v136
	v_add_f32_e32 v88, v97, v137
	s_waitcnt lgkmcnt(13)
	v_add_f32_e32 v163, v92, v167
	v_add_f32_e32 v164, v92, v166
	v_max3_f32 v84, v84, v87, v88
	v_add_f32_e32 v89, v98, v163
	v_add_f32_e32 v90, v99, v164
	s_waitcnt lgkmcnt(12)
	v_add_f32_e32 v165, v92, v169
	v_add_f32_e32 v166, v92, v168
	v_max3_f32 v84, v84, v89, v90
	v_add_f32_e32 v91, v100, v165
	v_add_f32_e32 v93, v101, v166
	s_waitcnt lgkmcnt(11)
	v_add_f32_e32 v167, v92, v171
	v_add_f32_e32 v168, v92, v170
	v_max3_f32 v84, v84, v91, v93
	v_add_f32_e32 v94, v102, v167
	v_add_f32_e32 v95, v103, v168
	s_waitcnt lgkmcnt(10)
	v_add_f32_e32 v169, v92, v173
	v_add_f32_e32 v170, v92, v172
	v_max3_f32 v84, v84, v94, v95
	v_add_f32_e32 v96, v104, v169
	v_add_f32_e32 v97, v105, v170
	s_waitcnt lgkmcnt(9)
	v_add_f32_e32 v98, v92, v39
	v_add_f32_e32 v99, v92, v38
	v_max3_f32 v84, v84, v96, v97
	v_add_f32_e32 v98, v106, v98
	v_add_f32_e32 v99, v107, v99
	s_waitcnt lgkmcnt(8)
	v_add_f32_e32 v100, v92, v37
	v_add_f32_e32 v101, v92, v36
	v_max3_f32 v84, v84, v98, v99
	v_add_f32_e32 v100, v108, v100
	v_add_f32_e32 v101, v109, v101
	s_waitcnt lgkmcnt(7)
	v_add_f32_e32 v171, 0, v175
	v_add_f32_e32 v172, 0, v174
	v_max3_f32 v84, v84, v100, v101
	v_add_f32_e32 v198, v110, v171
	v_add_f32_e32 v199, v111, v172
	s_waitcnt lgkmcnt(6)
	v_add_f32_e32 v173, 0, v177
	v_add_f32_e32 v174, 0, v176
	v_max3_f32 v84, v84, v198, v199
	v_add_f32_e32 v210, v112, v173
	v_add_f32_e32 v211, v113, v174
	s_waitcnt lgkmcnt(5)
	v_add_f32_e32 v175, 0, v179
	v_add_f32_e32 v176, 0, v178
	s_waitcnt lgkmcnt(3)
	v_add_f32_e32 v179, 0, v191
	v_max3_f32 v84, v84, v210, v211
	v_add_f32_e32 v212, v114, v175
	v_add_f32_e32 v213, v115, v176
	v_add_f32_e32 v177, 0, v189
	v_add_f32_e32 v178, 0, v188
	v_add_f32_e32 v191, v180, v179
	v_add_f32_e32 v180, 0, v190
	v_max3_f32 v84, v84, v212, v213
	v_add_f32_e32 v189, v116, v177
	v_add_f32_e32 v188, v117, v178
	v_add_f32_e32 v190, v181, v180
	s_waitcnt lgkmcnt(2)
	v_add_f32_e32 v181, 0, v193
	s_waitcnt lgkmcnt(1)
	v_add_f32_e32 v102, 0, v195
	v_max3_f32 v84, v84, v189, v188
	v_add_f32_e32 v193, v182, v181
	v_add_f32_e32 v182, 0, v192
	v_add_f32_e32 v184, v184, v102
	v_add_f32_e32 v102, 0, v194
	v_max3_f32 v84, v84, v191, v190
	v_add_f32_e32 v183, v183, v182
	v_add_f32_e32 v185, v185, v102
	s_waitcnt lgkmcnt(0)
	v_add_f32_e32 v102, 0, v197
	v_max3_f32 v84, v84, v193, v183
	v_add_f32_e32 v186, v186, v102
	v_add_f32_e32 v102, 0, v196
	v_max3_f32 v84, v84, v184, v185
	v_add_f32_e32 v187, v187, v102
	v_max3_f32 v84, v84, v186, v187
	ds_bpermute_b32 v102, v140, v84
	v_add_f32_e32 v52, v52, v118
	v_add_f32_e32 v53, v53, v119
	v_add_f32_e32 v54, v54, v120
	v_add_f32_e32 v55, v55, v121
	s_waitcnt lgkmcnt(0)
	v_max_f32_e32 v102, v102, v102
	v_max_f32_e32 v84, v84, v102
	ds_bpermute_b32 v102, v141, v84
	v_add_f32_e32 v56, v56, v122
	v_add_f32_e32 v57, v57, v123
	v_add_f32_e32 v58, v58, v124
	v_add_f32_e32 v59, v59, v125
	s_waitcnt lgkmcnt(0)
	v_max3_f32 v192, v84, v102, v133
	v_sub_f32_e32 v41, v41, v192
	v_exp_f32_e32 v110, v41
	v_sub_f32_e32 v40, v40, v192
	v_exp_f32_e32 v111, v40
	v_sub_f32_e32 v84, v187, v192
	v_add_f32_e32 v41, 0, v110
	v_exp_f32_e32 v84, v84
	v_add_f32_e32 v40, v111, v41
	v_sub_f32_e32 v41, v43, v192
	v_exp_f32_e32 v112, v41
	v_sub_f32_e32 v41, v42, v192
	v_exp_f32_e32 v113, v41
	v_sub_f32_e32 v41, v45, v192
	v_exp_f32_e32 v114, v41
	v_sub_f32_e32 v41, v44, v192
	v_exp_f32_e32 v115, v41
	v_sub_f32_e32 v41, v47, v192
	v_add_f32_e32 v40, v112, v40
	v_exp_f32_e32 v116, v41
	v_sub_f32_e32 v41, v46, v192
	v_add_f32_e32 v40, v113, v40
	v_exp_f32_e32 v117, v41
	v_sub_f32_e32 v41, v85, v192
	v_add_f32_e32 v40, v114, v40
	v_exp_f32_e32 v102, v41
	v_sub_f32_e32 v41, v86, v192
	v_add_f32_e32 v40, v115, v40
	v_exp_f32_e32 v103, v41
	v_sub_f32_e32 v41, v87, v192
	v_add_f32_e32 v40, v116, v40
	v_exp_f32_e32 v104, v41
	v_sub_f32_e32 v41, v88, v192
	v_add_f32_e32 v40, v117, v40
	v_exp_f32_e32 v105, v41
	v_sub_f32_e32 v41, v89, v192
	v_add_f32_e32 v40, v102, v40
	v_exp_f32_e32 v106, v41
	v_sub_f32_e32 v41, v90, v192
	v_add_f32_e32 v40, v103, v40
	v_exp_f32_e32 v107, v41
	v_sub_f32_e32 v41, v91, v192
	v_add_f32_e32 v40, v104, v40
	v_exp_f32_e32 v108, v41
	v_sub_f32_e32 v41, v93, v192
	v_add_f32_e32 v40, v105, v40
	v_exp_f32_e32 v109, v41
	v_sub_f32_e32 v41, v94, v192
	v_add_f32_e32 v40, v106, v40
	v_exp_f32_e32 v94, v41
	v_sub_f32_e32 v41, v95, v192
	v_add_f32_e32 v40, v107, v40
	v_exp_f32_e32 v95, v41
	v_sub_f32_e32 v41, v96, v192
	v_add_f32_e32 v40, v108, v40
	v_exp_f32_e32 v96, v41
	v_sub_f32_e32 v41, v97, v192
	v_add_f32_e32 v40, v109, v40
	v_exp_f32_e32 v97, v41
	v_sub_f32_e32 v41, v98, v192
	v_add_f32_e32 v40, v94, v40
	v_exp_f32_e32 v98, v41
	v_sub_f32_e32 v41, v99, v192
	v_add_f32_e32 v40, v95, v40
	v_exp_f32_e32 v99, v41
	v_sub_f32_e32 v41, v100, v192
	v_add_f32_e32 v40, v96, v40
	v_exp_f32_e32 v100, v41
	v_sub_f32_e32 v41, v101, v192
	v_add_f32_e32 v40, v97, v40
	v_exp_f32_e32 v101, v41
	v_sub_f32_e32 v41, v198, v192
	v_add_f32_e32 v40, v98, v40
	v_exp_f32_e32 v85, v41
	v_sub_f32_e32 v41, v199, v192
	v_add_f32_e32 v40, v99, v40
	v_exp_f32_e32 v86, v41
	v_sub_f32_e32 v41, v210, v192
	v_add_f32_e32 v40, v100, v40
	v_exp_f32_e32 v87, v41
	v_sub_f32_e32 v41, v211, v192
	v_add_f32_e32 v40, v101, v40
	v_exp_f32_e32 v88, v41
	v_sub_f32_e32 v41, v212, v192
	v_add_f32_e32 v40, v85, v40
	v_exp_f32_e32 v89, v41
	v_sub_f32_e32 v41, v213, v192
	v_add_f32_e32 v40, v86, v40
	v_exp_f32_e32 v90, v41
	v_sub_f32_e32 v41, v189, v192
	v_add_f32_e32 v40, v87, v40
	v_exp_f32_e32 v91, v41
	v_sub_f32_e32 v41, v188, v192
	v_add_f32_e32 v40, v88, v40
	v_exp_f32_e32 v93, v41
	v_sub_f32_e32 v41, v191, v192
	v_add_f32_e32 v40, v89, v40
	v_exp_f32_e32 v41, v41
	v_sub_f32_e32 v42, v190, v192
	v_add_f32_e32 v40, v90, v40
	v_exp_f32_e32 v42, v42
	v_sub_f32_e32 v43, v193, v192
	v_add_f32_e32 v40, v91, v40
	v_exp_f32_e32 v43, v43
	v_sub_f32_e32 v44, v183, v192
	v_add_f32_e32 v40, v93, v40
	v_exp_f32_e32 v44, v44
	v_sub_f32_e32 v45, v184, v192
	v_add_f32_e32 v40, v41, v40
	v_exp_f32_e32 v45, v45
	v_sub_f32_e32 v46, v185, v192
	v_add_f32_e32 v40, v42, v40
	v_exp_f32_e32 v46, v46
	v_sub_f32_e32 v47, v186, v192
	v_add_f32_e32 v40, v43, v40
	v_exp_f32_e32 v47, v47
	v_add_f32_e32 v40, v44, v40
	v_add_f32_e32 v40, v45, v40
	v_add_f32_e32 v40, v46, v40
	v_add_f32_e32 v40, v47, v40
	v_add_f32_e32 v40, v84, v40
	ds_bpermute_b32 v183, v140, v40
	v_add_f32_e32 v60, v60, v126
	v_add_f32_e32 v61, v61, v127
	v_add_f32_e32 v62, v62, v136
	v_add_f32_e32 v63, v63, v137
	s_waitcnt lgkmcnt(0)
	v_add_f32_e32 v40, v40, v183
	ds_bpermute_b32 v183, v141, v40
	v_add_f32_e32 v64, v64, v163
	v_add_f32_e32 v119, v65, v164
	v_add_f32_e32 v120, v67, v166
	v_add_f32_e32 v121, v68, v167
	s_waitcnt lgkmcnt(0)
	v_add_f32_e32 v40, v40, v183
	v_fma_f32 v183, v162, s6, -v192
	v_exp_f32_e32 v183, v183
	v_add_f32_e32 v122, v69, v168
	v_add_f32_e32 v123, v70, v169
	v_add_f32_e32 v124, v71, v170
	v_add_f32_e32 v40, v183, v40
	v_div_scale_f32 v183, s[0:1], v40, v40, 1.0
	v_rcp_f32_e32 v184, v183
	v_add_f32_e32 v39, 0, v39
	v_add_f32_e32 v38, 0, v38
	v_add_f32_e32 v39, v72, v39
	v_fma_f32 v185, -v183, v184, 1.0
	v_fmac_f32_e32 v184, v185, v184
	v_div_scale_f32 v185, vcc, 1.0, v40, 1.0
	v_mul_f32_e32 v186, v185, v184
	v_fma_f32 v187, -v183, v186, v185
	v_fmac_f32_e32 v186, v187, v184
	v_fma_f32 v183, -v183, v186, v185
	v_div_fmas_f32 v183, v183, v184, v186
	ds_read2_b32 v[184:185], v139 offset0:175 offset1:176
	ds_read2_b32 v[186:187], v139 offset0:173 offset1:174
	v_div_fixup_f32 v40, v183, v40, 1.0
	v_add_f32_e32 v38, v73, v38
	v_add_f32_e32 v37, 0, v37
	s_waitcnt lgkmcnt(1)
	v_add_f32_e32 v183, v92, v185
	v_add_f32_e32 v48, v48, v183
	v_add_f32_e32 v183, v92, v184
	s_waitcnt lgkmcnt(0)
	v_add_f32_e32 v184, v92, v187
	v_add_f32_e32 v49, v49, v183
	v_add_f32_e32 v50, v50, v184
	v_add_f32_e32 v184, v92, v186
	v_max3_f32 v183, v48, s7, v49
	v_add_f32_e32 v51, v51, v184
	v_max3_f32 v183, v183, v50, v51
	v_max3_f32 v118, v183, v52, v53
	v_max3_f32 v118, v118, v54, v55
	v_max3_f32 v118, v118, v56, v57
	v_max3_f32 v118, v118, v58, v59
	v_max3_f32 v118, v118, v60, v61
	v_max3_f32 v118, v118, v62, v63
	v_max3_f32 v65, v118, v64, v119
	v_add_f32_e32 v118, v66, v165
	v_max3_f32 v65, v65, v118, v120
	v_max3_f32 v65, v65, v121, v122
	v_max3_f32 v65, v65, v123, v124
	v_add_f32_e32 v36, 0, v36
	v_max3_f32 v65, v65, v39, v38
	v_add_f32_e32 v37, v74, v37
	v_add_f32_e32 v36, v75, v36
	v_max3_f32 v65, v65, v37, v36
	v_add_f32_e32 v125, v76, v171
	v_add_f32_e32 v126, v77, v172
	v_max3_f32 v65, v65, v125, v126
	v_add_f32_e32 v127, v78, v173
	v_add_f32_e32 v136, v79, v174
	v_max3_f32 v65, v65, v127, v136
	v_add_f32_e32 v137, v80, v175
	v_add_f32_e32 v81, v81, v176
	v_max3_f32 v65, v65, v137, v81
	v_add_f32_e32 v82, v82, v177
	v_add_f32_e32 v83, v83, v178
	v_max3_f32 v65, v65, v82, v83
	v_add_f32_e32 v32, v32, v179
	v_add_f32_e32 v163, v33, v180
	v_max3_f32 v33, v65, v32, v163
	v_add_f32_e32 v164, v34, v181
	v_add_f32_e32 v165, v35, v182
	v_max3_f32 v33, v33, v164, v165
	ds_bpermute_b32 v34, v140, v33
	v_cvt_pk_bf16_f32 v110, v110, v111
	v_cvt_pk_bf16_f32 v111, v112, v113
	v_cvt_pk_bf16_f32 v112, v114, v115
	v_cvt_pk_bf16_f32 v113, v116, v117
	s_waitcnt lgkmcnt(0)
	v_max_f32_e32 v34, v34, v34
	v_max_f32_e32 v33, v33, v34
	ds_bpermute_b32 v34, v141, v33
	s_waitcnt lgkmcnt(0)
	v_max3_f32 v166, v33, v34, v133
	v_sub_f32_e32 v33, v48, v166
	v_exp_f32_e32 v73, v33
	v_sub_f32_e32 v34, v49, v166
	v_exp_f32_e32 v74, v34
	v_sub_f32_e32 v34, v50, v166
	v_exp_f32_e32 v75, v34
	v_sub_f32_e32 v34, v51, v166
	v_exp_f32_e32 v76, v34
	v_sub_f32_e32 v34, v52, v166
	v_add_f32_e32 v33, 0, v73
	v_exp_f32_e32 v77, v34
	v_sub_f32_e32 v34, v53, v166
	v_add_f32_e32 v33, v74, v33
	v_exp_f32_e32 v78, v34
	v_sub_f32_e32 v34, v54, v166
	v_add_f32_e32 v33, v75, v33
	v_exp_f32_e32 v79, v34
	v_sub_f32_e32 v34, v55, v166
	v_add_f32_e32 v33, v76, v33
	v_exp_f32_e32 v80, v34
	v_sub_f32_e32 v34, v56, v166
	v_add_f32_e32 v33, v77, v33
	v_exp_f32_e32 v65, v34
	v_sub_f32_e32 v34, v57, v166
	v_add_f32_e32 v33, v78, v33
	v_exp_f32_e32 v66, v34
	v_sub_f32_e32 v34, v58, v166
	v_add_f32_e32 v33, v79, v33
	v_exp_f32_e32 v67, v34
	v_sub_f32_e32 v34, v59, v166
	v_add_f32_e32 v33, v80, v33
	v_exp_f32_e32 v68, v34
	v_sub_f32_e32 v34, v60, v166
	v_add_f32_e32 v33, v65, v33
	v_exp_f32_e32 v69, v34
	v_sub_f32_e32 v34, v61, v166
	v_add_f32_e32 v33, v66, v33
	v_exp_f32_e32 v70, v34
	v_sub_f32_e32 v34, v62, v166
	v_add_f32_e32 v33, v67, v33
	v_exp_f32_e32 v71, v34
	v_sub_f32_e32 v34, v63, v166
	v_add_f32_e32 v33, v68, v33
	v_exp_f32_e32 v72, v34
	v_sub_f32_e32 v34, v64, v166
	v_add_f32_e32 v33, v69, v33
	v_exp_f32_e32 v57, v34
	v_sub_f32_e32 v34, v119, v166
	v_add_f32_e32 v33, v70, v33
	v_exp_f32_e32 v58, v34
	v_sub_f32_e32 v34, v118, v166
	v_add_f32_e32 v33, v71, v33
	v_exp_f32_e32 v59, v34
	v_sub_f32_e32 v34, v120, v166
	v_add_f32_e32 v33, v72, v33
	v_exp_f32_e32 v60, v34
	v_sub_f32_e32 v34, v121, v166
	v_add_f32_e32 v33, v57, v33
	v_exp_f32_e32 v61, v34
	v_sub_f32_e32 v34, v122, v166
	v_add_f32_e32 v33, v58, v33
	v_exp_f32_e32 v62, v34
	v_sub_f32_e32 v34, v123, v166
	v_add_f32_e32 v33, v59, v33
	v_exp_f32_e32 v63, v34
	v_sub_f32_e32 v34, v124, v166
	v_add_f32_e32 v33, v60, v33
	v_exp_f32_e32 v64, v34
	v_sub_f32_e32 v34, v39, v166
	v_add_f32_e32 v33, v61, v33
	v_exp_f32_e32 v49, v34
	v_sub_f32_e32 v34, v38, v166
	v_add_f32_e32 v33, v62, v33
	v_exp_f32_e32 v50, v34
	v_sub_f32_e32 v34, v37, v166
	v_add_f32_e32 v33, v63, v33
	v_exp_f32_e32 v51, v34
	v_sub_f32_e32 v34, v36, v166
	v_add_f32_e32 v33, v64, v33
	v_exp_f32_e32 v52, v34
	v_sub_f32_e32 v34, v125, v166
	v_add_f32_e32 v33, v49, v33
	v_exp_f32_e32 v53, v34
	v_sub_f32_e32 v34, v126, v166
	v_add_f32_e32 v33, v50, v33
	v_exp_f32_e32 v54, v34
	v_sub_f32_e32 v34, v127, v166
	v_add_f32_e32 v33, v51, v33
	v_exp_f32_e32 v55, v34
	v_sub_f32_e32 v34, v136, v166
	v_add_f32_e32 v33, v52, v33
	v_exp_f32_e32 v56, v34
	v_add_f32_e32 v33, v53, v33
	v_add_f32_e32 v33, v54, v33
	v_add_f32_e32 v33, v55, v33
	v_add_f32_e32 v34, v56, v33
	v_sub_f32_e32 v33, v137, v166
	v_exp_f32_e32 v33, v33
	v_sub_f32_e32 v32, v32, v166
	v_sub_f32_e32 v39, v164, v166
	v_exp_f32_e32 v39, v39
	v_add_f32_e32 v35, v33, v34
	v_sub_f32_e32 v34, v81, v166
	v_exp_f32_e32 v34, v34
	v_sub_f32_e32 v48, v165, v166
	v_exp_f32_e32 v48, v48
	v_cvt_pk_bf16_f32 v74, v73, v74
	v_add_f32_e32 v36, v34, v35
	v_sub_f32_e32 v35, v82, v166
	v_exp_f32_e32 v35, v35
	v_cvt_pk_bf16_f32 v75, v75, v76
	v_cvt_pk_bf16_f32 v76, v77, v78
	v_cvt_pk_bf16_f32 v77, v79, v80
	ds_read_b128 v[172:175], v142 offset:62272
	v_add_f32_e32 v37, v35, v36
	v_sub_f32_e32 v36, v83, v166
	v_exp_f32_e32 v36, v36
	s_nop 0
	v_add_f32_e32 v38, v36, v37
	v_exp_f32_e32 v37, v32
	s_nop 0
	v_add_f32_e32 v32, v37, v38
	v_sub_f32_e32 v38, v163, v166
	v_exp_f32_e32 v38, v38
	s_nop 0
	v_add_f32_e32 v32, v38, v32
	v_add_f32_e32 v32, v39, v32
	v_add_f32_e32 v32, v48, v32
	ds_bpermute_b32 v81, v140, v32
	s_waitcnt lgkmcnt(0)
	v_add_f32_e32 v32, v32, v81
	ds_bpermute_b32 v81, v141, v32
	s_waitcnt lgkmcnt(0)
	v_add_f32_e32 v32, v32, v81
	v_fma_f32 v81, v162, s6, -v166
	v_exp_f32_e32 v81, v81
	ds_read_b128 v[164:167], v142 offset:53824
	s_waitcnt lgkmcnt(0)
	v_mfma_f32_16x16x32_bf16 v[168:171], v[164:167], v[110:113], 0
	v_add_f32_e32 v32, v81, v32
	v_div_scale_f32 v81, s[0:1], v32, v32, 1.0
	v_rcp_f32_e32 v82, v81
	v_mfma_f32_16x16x32_bf16 v[164:167], v[164:167], v[74:77], 0
	v_fma_f32 v83, -v81, v82, 1.0
	v_fmac_f32_e32 v82, v83, v82
	v_div_scale_f32 v83, vcc, 1.0, v32, 1.0
	v_mul_f32_e32 v118, v83, v82
	v_fma_f32 v119, -v81, v118, v83
	v_fmac_f32_e32 v118, v119, v82
	v_fma_f32 v81, -v81, v118, v83
	v_div_fmas_f32 v81, v81, v82, v118
	v_div_fixup_f32 v32, v81, v32, 1.0
	ds_read_b128 v[78:81], v142 offset:36928
	ds_read_b128 v[118:121], v142 offset:45376
	v_cvt_pk_bf16_f32 v102, v102, v103
	v_cvt_pk_bf16_f32 v103, v104, v105
	v_cvt_pk_bf16_f32 v104, v106, v107
	v_cvt_pk_bf16_f32 v105, v108, v109
	v_cvt_pk_bf16_f32 v66, v65, v66
	v_cvt_pk_bf16_f32 v67, v67, v68
	v_cvt_pk_bf16_f32 v68, v69, v70
	v_cvt_pk_bf16_f32 v69, v71, v72
	ds_read_b128 v[70:73], v142 offset:36992
	s_waitcnt lgkmcnt(2)
	v_mfma_f32_16x16x32_bf16 v[114:117], v[78:81], v[110:113], 0
	v_mfma_f32_16x16x32_bf16 v[78:81], v[78:81], v[74:77], 0
	s_waitcnt lgkmcnt(0)
	v_mfma_f32_16x16x32_bf16 v[106:109], v[70:73], v[102:105], v[114:117]
	v_mfma_f32_16x16x32_bf16 v[70:73], v[70:73], v[66:69], v[78:81]
	s_nop 4
	ds_read_b128 v[78:81], v142 offset:45440
	v_mfma_f32_16x16x32_bf16 v[122:125], v[118:121], v[110:113], 0
	v_mfma_f32_16x16x32_bf16 v[118:121], v[118:121], v[74:77], 0
	s_waitcnt lgkmcnt(0)
	v_mfma_f32_16x16x32_bf16 v[114:117], v[78:81], v[102:105], v[122:125]
	v_mfma_f32_16x16x32_bf16 v[78:81], v[78:81], v[66:69], v[118:121]
	s_nop 4
	ds_read_b128 v[118:121], v142 offset:53888
	s_waitcnt lgkmcnt(0)
	v_mfma_f32_16x16x32_bf16 v[122:125], v[118:121], v[102:105], v[168:171]
	v_mfma_f32_16x16x32_bf16 v[118:121], v[118:121], v[66:69], v[164:167]
	s_nop 2
	ds_read_b128 v[164:167], v142 offset:62336
	v_mfma_f32_16x16x32_bf16 v[74:77], v[172:175], v[74:77], 0
	s_waitcnt lgkmcnt(0)
	v_mfma_f32_16x16x32_bf16 v[66:69], v[164:167], v[66:69], v[74:77]
	v_cvt_pk_bf16_f32 v74, v94, v95
	v_cvt_pk_bf16_f32 v75, v96, v97
	v_cvt_pk_bf16_f32 v76, v98, v99
	v_cvt_pk_bf16_f32 v77, v100, v101
	v_cvt_pk_bf16_f32 v58, v57, v58
	v_cvt_pk_bf16_f32 v59, v59, v60
	v_cvt_pk_bf16_f32 v60, v61, v62
	v_cvt_pk_bf16_f32 v61, v63, v64
	ds_read_b128 v[62:65], v142 offset:37056
	v_mfma_f32_16x16x32_bf16 v[110:113], v[172:175], v[110:113], 0
	v_mfma_f32_16x16x32_bf16 v[102:105], v[164:167], v[102:105], v[110:113]
	s_nop 6
	ds_read_b128 v[110:113], v142 offset:62400
	s_waitcnt lgkmcnt(1)
	v_mfma_f32_16x16x32_bf16 v[94:97], v[62:65], v[74:77], v[106:109]
	v_mfma_f32_16x16x32_bf16 v[62:65], v[62:65], v[58:61], v[70:73]
	s_nop 2
	ds_read_b128 v[70:73], v142 offset:45504
	s_waitcnt lgkmcnt(0)
	v_mfma_f32_16x16x32_bf16 v[98:101], v[70:73], v[74:77], v[114:117]
	v_mfma_f32_16x16x32_bf16 v[70:73], v[70:73], v[58:61], v[78:81]
	s_nop 2
	ds_read_b128 v[78:81], v142 offset:53952
	s_waitcnt lgkmcnt(0)
	v_mfma_f32_16x16x32_bf16 v[106:109], v[78:81], v[74:77], v[122:125]
	v_mfma_f32_16x16x32_bf16 v[78:81], v[78:81], v[58:61], v[118:121]
	v_mfma_f32_16x16x32_bf16 v[58:61], v[110:113], v[58:61], v[66:69]
	v_cvt_pk_bf16_f32 v66, v85, v86
	v_cvt_pk_bf16_f32 v67, v87, v88
	v_cvt_pk_bf16_f32 v68, v89, v90
	v_cvt_pk_bf16_f32 v69, v91, v93
	v_cvt_pk_bf16_f32 v50, v49, v50
	v_cvt_pk_bf16_f32 v51, v51, v52
	v_cvt_pk_bf16_f32 v52, v53, v54
	v_cvt_pk_bf16_f32 v53, v55, v56
	ds_read_b128 v[54:57], v142 offset:37120
	s_waitcnt lgkmcnt(0)
	v_mfma_f32_16x16x32_bf16 v[86:89], v[54:57], v[66:69], v[94:97]
	v_mfma_f32_16x16x32_bf16 v[54:57], v[54:57], v[50:53], v[62:65]
	s_nop 2
	ds_read_b128 v[62:65], v142 offset:45568
	s_waitcnt lgkmcnt(0)
	v_mfma_f32_16x16x32_bf16 v[94:97], v[62:65], v[66:69], v[98:101]
	v_mfma_f32_16x16x32_bf16 v[62:65], v[62:65], v[50:53], v[70:73]
	s_nop 2
	ds_read_b128 v[70:73], v142 offset:54016
	s_waitcnt lgkmcnt(0)
	v_mfma_f32_16x16x32_bf16 v[98:101], v[70:73], v[66:69], v[106:109]
	v_mfma_f32_16x16x32_bf16 v[70:73], v[70:73], v[50:53], v[78:81]
	s_nop 2
	ds_read_b128 v[78:81], v142 offset:62464
	v_cvt_pk_bf16_f32 v42, v41, v42
	v_cvt_pk_bf16_f32 v43, v43, v44
	v_cvt_pk_bf16_f32 v44, v45, v46
	v_cvt_pk_bf16_f32 v45, v47, v84
	v_cvt_pk_bf16_f32 v34, v33, v34
	v_cvt_pk_bf16_f32 v35, v35, v36
	v_cvt_pk_bf16_f32 v36, v37, v38
	v_cvt_pk_bf16_f32 v37, v39, v48
	ds_read_b128 v[46:49], v142 offset:37184
	s_waitcnt lgkmcnt(1)
	v_mfma_f32_16x16x32_bf16 v[50:53], v[78:81], v[50:53], v[58:61]
	v_or_b32_e32 v38, 32, v132
	v_ashrrev_i32_e32 v39, 31, v38
	v_lshlrev_b64 v[38:39], 12, v[38:39]
	s_waitcnt lgkmcnt(0)
	v_mfma_f32_16x16x32_bf16 v[58:61], v[46:49], v[42:45], v[86:89]
	v_lshl_add_u64 v[38:39], v[134:135], 0, v[38:39]
	s_nop 6
	v_mul_f32_e32 v33, v40, v58
	v_mfma_f32_16x16x32_bf16 v[46:49], v[46:49], v[34:37], v[54:57]
	v_mul_f32_e32 v41, v40, v59
	s_nop 1
	ds_read_b128 v[54:57], v142 offset:45632
	v_mfma_f32_16x16x32_bf16 v[74:77], v[110:113], v[74:77], v[102:105]
	v_mfma_f32_16x16x32_bf16 v[66:69], v[78:81], v[66:69], v[74:77]
	s_waitcnt lgkmcnt(0)
	v_mfma_f32_16x16x32_bf16 v[74:77], v[54:57], v[42:45], v[94:97]
	v_mfma_f32_16x16x32_bf16 v[54:57], v[54:57], v[34:37], v[62:65]
	s_nop 2
	ds_read_b128 v[62:65], v142 offset:54080
	s_waitcnt lgkmcnt(0)
	v_mfma_f32_16x16x32_bf16 v[78:81], v[62:65], v[42:45], v[98:101]
	v_mfma_f32_16x16x32_bf16 v[62:65], v[62:65], v[34:37], v[70:73]
	s_nop 2
	ds_read_b128 v[70:73], v142 offset:62528
	s_waitcnt lgkmcnt(0)
	v_mfma_f32_16x16x32_bf16 v[34:37], v[70:73], v[34:37], v[50:53]
	v_cvt_pk_bf16_f32 v50, v33, v41
	v_mul_f32_e32 v33, v40, v60
	v_mul_f32_e32 v41, v40, v61
	v_mfma_f32_16x16x32_bf16 v[42:45], v[70:73], v[42:45], v[66:69]
	v_cvt_pk_bf16_f32 v51, v33, v41
	v_mul_f32_e32 v33, v40, v74
	global_store_dwordx2 v[38:39], v[50:51], off
	v_mul_f32_e32 v41, v40, v75
	v_cvt_pk_bf16_f32 v50, v33, v41
	v_mul_f32_e32 v33, v40, v76
	v_mul_f32_e32 v41, v40, v77
	v_cvt_pk_bf16_f32 v51, v33, v41
	v_mul_f32_e32 v33, v40, v78
	global_store_dwordx2 v[38:39], v[50:51], off offset:32
	v_mul_f32_e32 v41, v40, v79
	v_cvt_pk_bf16_f32 v50, v33, v41
	v_mul_f32_e32 v33, v40, v80
	v_mul_f32_e32 v41, v40, v81
	v_cvt_pk_bf16_f32 v51, v33, v41
	v_mul_f32_e32 v33, v40, v42
	global_store_dwordx2 v[38:39], v[50:51], off offset:64
	v_mul_f32_e32 v41, v40, v43
	v_cvt_pk_bf16_f32 v42, v33, v41
	v_mul_f32_e32 v33, v40, v44
	v_mul_f32_e32 v40, v40, v45
	v_cvt_pk_bf16_f32 v43, v33, v40
	global_store_dwordx2 v[38:39], v[42:43], off offset:96
	v_or_b32_e32 v38, 48, v132
	v_ashrrev_i32_e32 v39, 31, v38
	v_lshlrev_b64 v[38:39], 12, v[38:39]
	v_mul_f32_e32 v33, v32, v46
	v_mul_f32_e32 v40, v32, v47
	v_lshl_add_u64 v[38:39], v[134:135], 0, v[38:39]
	v_cvt_pk_bf16_f32 v40, v33, v40
	v_mul_f32_e32 v33, v32, v48
	v_mul_f32_e32 v41, v32, v49
	v_cvt_pk_bf16_f32 v41, v33, v41
	global_store_dwordx2 v[38:39], v[40:41], off
	v_mul_f32_e32 v33, v32, v54
	v_mul_f32_e32 v40, v32, v55
	v_cvt_pk_bf16_f32 v40, v33, v40
	v_mul_f32_e32 v33, v32, v56
	v_mul_f32_e32 v41, v32, v57
	v_cvt_pk_bf16_f32 v41, v33, v41
	global_store_dwordx2 v[38:39], v[40:41], off offset:32
	v_mul_f32_e32 v33, v32, v62
	v_mul_f32_e32 v40, v32, v63
	v_cvt_pk_bf16_f32 v40, v33, v40
	v_mul_f32_e32 v33, v32, v64
	v_mul_f32_e32 v41, v32, v65
	v_cvt_pk_bf16_f32 v41, v33, v41
	v_mul_f32_e32 v33, v32, v34
	v_mul_f32_e32 v34, v32, v35
	global_store_dwordx2 v[38:39], v[40:41], off offset:64
	v_cvt_pk_bf16_f32 v34, v33, v34
	v_mul_f32_e32 v33, v32, v36
	v_mul_f32_e32 v32, v32, v37
	v_cvt_pk_bf16_f32 v35, v33, v32
	global_store_dwordx2 v[38:39], v[34:35], off offset:96
	ds_read_b128 v[32:35], v153 offset:9216
	ds_read_b128 v[36:39], v153 offset:9280
	s_waitcnt vmcnt(23) lgkmcnt(1)
	v_mfma_f32_16x16x32_bf16 v[40:43], v[32:35], v[20:23], 0
	s_waitcnt vmcnt(21)
	v_mfma_f32_16x16x32_bf16 v[32:35], v[32:35], v[24:27], 0
	s_waitcnt lgkmcnt(0)
	v_mfma_f32_16x16x32_bf16 v[68:71], v[36:39], v[16:19], v[40:43]
	s_waitcnt vmcnt(20)
	v_mfma_f32_16x16x32_bf16 v[32:35], v[36:39], v[28:31], v[32:35]
	ds_read_b128 v[36:39], v153 offset:11520
	s_nop 0
	ds_read_b128 v[40:43], v153 offset:11584
	s_waitcnt lgkmcnt(1)
	v_mfma_f32_16x16x32_bf16 v[44:47], v[36:39], v[20:23], 0
	v_mfma_f32_16x16x32_bf16 v[36:39], v[36:39], v[24:27], 0
	s_waitcnt lgkmcnt(0)
	v_mfma_f32_16x16x32_bf16 v[72:75], v[40:43], v[16:19], v[44:47]
	v_mfma_f32_16x16x32_bf16 v[36:39], v[40:43], v[28:31], v[36:39]
	ds_read_b128 v[40:43], v153 offset:13824
	s_nop 2
	ds_read_b128 v[44:47], v153 offset:13888
	s_waitcnt lgkmcnt(1)
	v_mfma_f32_16x16x32_bf16 v[48:51], v[40:43], v[20:23], 0
	v_mfma_f32_16x16x32_bf16 v[40:43], v[40:43], v[24:27], 0
	s_waitcnt lgkmcnt(0)
	v_mfma_f32_16x16x32_bf16 v[76:79], v[44:47], v[16:19], v[48:51]
	v_mfma_f32_16x16x32_bf16 v[40:43], v[44:47], v[28:31], v[40:43]
	ds_read_b128 v[44:47], v153 offset:16128
	s_nop 2
	ds_read_b128 v[48:51], v153 offset:16192
	s_waitcnt lgkmcnt(1)
	v_mfma_f32_16x16x32_bf16 v[52:55], v[44:47], v[20:23], 0
	v_mfma_f32_16x16x32_bf16 v[44:47], v[44:47], v[24:27], 0
	s_waitcnt lgkmcnt(0)
	v_mfma_f32_16x16x32_bf16 v[80:83], v[48:51], v[16:19], v[52:55]
	v_mfma_f32_16x16x32_bf16 v[44:47], v[48:51], v[28:31], v[44:47]
	ds_read_b128 v[48:51], v153 offset:18432
	s_nop 2
	ds_read_b128 v[52:55], v153 offset:18496
	s_waitcnt lgkmcnt(1)
	v_mfma_f32_16x16x32_bf16 v[56:59], v[48:51], v[20:23], 0
	v_mfma_f32_16x16x32_bf16 v[48:51], v[48:51], v[24:27], 0
	s_waitcnt lgkmcnt(0)
	v_mfma_f32_16x16x32_bf16 v[84:87], v[52:55], v[16:19], v[56:59]
	v_mfma_f32_16x16x32_bf16 v[48:51], v[52:55], v[28:31], v[48:51]
	ds_read_b128 v[52:55], v153 offset:20736
	s_nop 2
	ds_read_b128 v[56:59], v153 offset:20800
	s_waitcnt lgkmcnt(1)
	v_mfma_f32_16x16x32_bf16 v[60:63], v[52:55], v[20:23], 0
	v_mfma_f32_16x16x32_bf16 v[52:55], v[52:55], v[24:27], 0
	s_waitcnt lgkmcnt(0)
	v_mfma_f32_16x16x32_bf16 v[88:91], v[56:59], v[16:19], v[60:63]
	v_mfma_f32_16x16x32_bf16 v[52:55], v[56:59], v[28:31], v[52:55]
	ds_read_b128 v[56:59], v153 offset:23040
	s_nop 2
	ds_read_b128 v[60:63], v153 offset:23104
	s_waitcnt lgkmcnt(1)
	v_mfma_f32_16x16x32_bf16 v[64:67], v[56:59], v[20:23], 0
	v_mfma_f32_16x16x32_bf16 v[56:59], v[56:59], v[24:27], 0
	s_waitcnt lgkmcnt(0)
	v_mfma_f32_16x16x32_bf16 v[94:97], v[60:63], v[16:19], v[64:67]
	v_mfma_f32_16x16x32_bf16 v[56:59], v[60:63], v[28:31], v[56:59]
	ds_read_b128 v[60:63], v153 offset:25344
	s_nop 2
	ds_read_b128 v[64:67], v153 offset:25408
	s_waitcnt lgkmcnt(1)
	v_mfma_f32_16x16x32_bf16 v[98:101], v[60:63], v[20:23], 0
	v_mfma_f32_16x16x32_bf16 v[60:63], v[60:63], v[24:27], 0
	s_waitcnt lgkmcnt(0)
	v_mfma_f32_16x16x32_bf16 v[98:101], v[64:67], v[16:19], v[98:101]
	v_mfma_f32_16x16x32_bf16 v[60:63], v[64:67], v[28:31], v[60:63]
	ds_read_b128 v[64:67], v153 offset:27648
	ds_read_b128 v[102:105], v153 offset:27712
	s_waitcnt lgkmcnt(1)
	v_mfma_f32_16x16x32_bf16 v[106:109], v[64:67], v[20:23], 0
	v_mfma_f32_16x16x32_bf16 v[64:67], v[64:67], v[24:27], 0
	s_waitcnt lgkmcnt(0)
	v_mfma_f32_16x16x32_bf16 v[164:167], v[102:105], v[16:19], v[106:109]
	v_mfma_f32_16x16x32_bf16 v[64:67], v[102:105], v[28:31], v[64:67]
	ds_read_b128 v[102:105], v153 offset:29952
	s_nop 2
	ds_read_b128 v[106:109], v153 offset:30016
	s_waitcnt lgkmcnt(1)
	v_mfma_f32_16x16x32_bf16 v[20:23], v[102:105], v[20:23], 0
	s_waitcnt lgkmcnt(0)
	v_mfma_f32_16x16x32_bf16 v[168:171], v[106:109], v[16:19], v[20:23]
	v_mfma_f32_16x16x32_bf16 v[16:19], v[102:105], v[24:27], 0
	v_mfma_f32_16x16x32_bf16 v[16:19], v[106:109], v[28:31], v[16:19]
	ds_read2_b32 v[24:25], v139 offset0:159 offset1:160
	ds_read2_b32 v[26:27], v139 offset0:157 offset1:158
	ds_read2_b32 v[28:29], v139 offset0:143 offset1:144
	ds_read2_b32 v[30:31], v139 offset0:141 offset1:142
	ds_read2_b32 v[112:113], v139 offset0:127 offset1:128
	ds_read2_b32 v[114:115], v139 offset0:125 offset1:126
	ds_read2_b32 v[22:23], v139 offset0:111 offset1:112
	ds_read2_b32 v[20:21], v139 offset0:109 offset1:110
	ds_read2_b32 v[116:117], v139 offset0:95 offset1:96
	ds_read2_b32 v[118:119], v139 offset0:93 offset1:94
	ds_read2_b32 v[120:121], v139 offset0:79 offset1:80
	ds_read2_b32 v[122:123], v139 offset0:77 offset1:78
	ds_read2_b32 v[124:125], v139 offset0:63 offset1:64
	ds_read2_b32 v[126:127], v139 offset0:61 offset1:62
	ds_read2_b32 v[136:137], v139 offset0:47 offset1:48
	ds_read2_b32 v[172:173], v139 offset0:45 offset1:46
	ds_read2_b32 v[174:175], v139 offset0:31 offset1:32
	ds_read2_b32 v[176:177], v139 offset0:29 offset1:30
	ds_read2_b32 v[178:179], v139 offset0:15 offset1:16
	ds_read2_b32 v[180:181], v139 offset0:13 offset1:14
	s_waitcnt lgkmcnt(14)
	v_add_f32_e32 v102, v92, v25
	v_add_f32_e32 v103, v92, v24
	v_add_f32_e32 v25, v68, v102
	v_add_f32_e32 v24, v69, v103
	v_add_f32_e32 v104, v92, v27
	v_add_f32_e32 v105, v92, v26
	v_max3_f32 v68, v25, s7, v24
	v_add_f32_e32 v27, v70, v104
	v_add_f32_e32 v26, v71, v105
	v_add_f32_e32 v106, v92, v29
	v_add_f32_e32 v107, v92, v28
	v_max3_f32 v68, v68, v27, v26
	v_add_f32_e32 v29, v72, v106
	v_add_f32_e32 v28, v73, v107
	v_add_f32_e32 v108, v92, v31
	v_add_f32_e32 v109, v92, v30
	v_max3_f32 v68, v68, v29, v28
	v_add_f32_e32 v31, v74, v108
	v_add_f32_e32 v30, v75, v109
	v_add_f32_e32 v110, v92, v113
	v_add_f32_e32 v111, v92, v112
	v_max3_f32 v68, v68, v31, v30
	v_add_f32_e32 v69, v76, v110
	v_add_f32_e32 v70, v77, v111
	v_add_f32_e32 v112, v92, v115
	v_add_f32_e32 v113, v92, v114
	v_max3_f32 v68, v68, v69, v70
	v_add_f32_e32 v71, v78, v112
	v_add_f32_e32 v72, v79, v113
	s_waitcnt lgkmcnt(13)
	v_add_f32_e32 v73, v92, v23
	v_add_f32_e32 v74, v92, v22
	v_max3_f32 v68, v68, v71, v72
	v_add_f32_e32 v73, v80, v73
	v_add_f32_e32 v74, v81, v74
	s_waitcnt lgkmcnt(12)
	v_add_f32_e32 v75, v92, v21
	v_add_f32_e32 v76, v92, v20
	v_max3_f32 v68, v68, v73, v74
	v_add_f32_e32 v75, v82, v75
	v_add_f32_e32 v76, v83, v76
	s_waitcnt lgkmcnt(11)
	v_add_f32_e32 v114, 0, v117
	v_add_f32_e32 v115, 0, v116
	v_max3_f32 v68, v68, v75, v76
	v_add_f32_e32 v77, v84, v114
	v_add_f32_e32 v78, v85, v115
	s_waitcnt lgkmcnt(10)
	v_add_f32_e32 v116, 0, v119
	v_add_f32_e32 v117, 0, v118
	v_max3_f32 v68, v68, v77, v78
	v_add_f32_e32 v79, v86, v116
	v_add_f32_e32 v80, v87, v117
	s_waitcnt lgkmcnt(9)
	v_add_f32_e32 v118, 0, v121
	v_add_f32_e32 v119, 0, v120
	v_max3_f32 v68, v68, v79, v80
	v_add_f32_e32 v81, v88, v118
	v_add_f32_e32 v82, v89, v119
	s_waitcnt lgkmcnt(8)
	v_add_f32_e32 v120, 0, v123
	v_add_f32_e32 v121, 0, v122
	v_max3_f32 v68, v68, v81, v82
	v_add_f32_e32 v83, v90, v120
	v_add_f32_e32 v84, v91, v121
	s_waitcnt lgkmcnt(7)
	v_add_f32_e32 v122, 0, v125
	v_add_f32_e32 v123, 0, v124
	v_max3_f32 v68, v68, v83, v84
	v_add_f32_e32 v182, v94, v122
	v_add_f32_e32 v183, v95, v123
	s_waitcnt lgkmcnt(6)
	v_add_f32_e32 v124, 0, v127
	v_add_f32_e32 v125, 0, v126
	v_max3_f32 v68, v68, v182, v183
	v_add_f32_e32 v184, v96, v124
	v_add_f32_e32 v185, v97, v125
	s_waitcnt lgkmcnt(5)
	v_add_f32_e32 v126, 0, v137
	v_add_f32_e32 v127, 0, v136
	s_waitcnt lgkmcnt(3)
	v_add_f32_e32 v163, 0, v175
	v_max3_f32 v68, v68, v184, v185
	v_add_f32_e32 v186, v98, v126
	v_add_f32_e32 v187, v99, v127
	v_add_f32_e32 v136, 0, v173
	v_add_f32_e32 v137, 0, v172
	v_add_f32_e32 v175, v164, v163
	v_add_f32_e32 v164, 0, v174
	v_max3_f32 v68, v68, v186, v187
	v_add_f32_e32 v173, v100, v136
	v_add_f32_e32 v172, v101, v137
	v_add_f32_e32 v174, v165, v164
	s_waitcnt lgkmcnt(2)
	v_add_f32_e32 v165, 0, v177
	s_waitcnt lgkmcnt(1)
	v_add_f32_e32 v85, 0, v179
	v_max3_f32 v68, v68, v173, v172
	v_add_f32_e32 v177, v166, v165
	v_add_f32_e32 v166, 0, v176
	v_add_f32_e32 v168, v168, v85
	v_add_f32_e32 v85, 0, v178
	v_max3_f32 v68, v68, v175, v174
	v_add_f32_e32 v167, v167, v166
	v_add_f32_e32 v169, v169, v85
	s_waitcnt lgkmcnt(0)
	v_add_f32_e32 v85, 0, v181
	v_max3_f32 v68, v68, v177, v167
	v_add_f32_e32 v170, v170, v85
	v_add_f32_e32 v85, 0, v180
	v_max3_f32 v68, v68, v168, v169
	v_add_f32_e32 v171, v171, v85
	v_max3_f32 v68, v68, v170, v171
	ds_bpermute_b32 v85, v140, v68
	v_add_f32_e32 v36, v36, v102
	v_add_f32_e32 v37, v37, v103
	v_add_f32_e32 v38, v38, v104
	v_add_f32_e32 v39, v39, v105
	s_waitcnt lgkmcnt(0)
	v_max_f32_e32 v85, v85, v85
	v_max_f32_e32 v68, v68, v85
	ds_bpermute_b32 v85, v141, v68
	v_add_f32_e32 v40, v40, v106
	v_add_f32_e32 v41, v41, v107
	v_add_f32_e32 v42, v42, v108
	v_add_f32_e32 v43, v43, v109
	s_waitcnt lgkmcnt(0)
	v_max3_f32 v176, v68, v85, v133
	v_sub_f32_e32 v25, v25, v176
	v_exp_f32_e32 v94, v25
	v_sub_f32_e32 v24, v24, v176
	v_exp_f32_e32 v95, v24
	v_sub_f32_e32 v68, v171, v176
	v_add_f32_e32 v25, 0, v94
	v_exp_f32_e32 v68, v68
	v_add_f32_e32 v24, v95, v25
	v_sub_f32_e32 v25, v27, v176
	v_exp_f32_e32 v96, v25
	v_sub_f32_e32 v25, v26, v176
	v_exp_f32_e32 v97, v25
	v_sub_f32_e32 v25, v29, v176
	v_exp_f32_e32 v98, v25
	v_sub_f32_e32 v25, v28, v176
	v_exp_f32_e32 v99, v25
	v_sub_f32_e32 v25, v31, v176
	v_add_f32_e32 v24, v96, v24
	v_exp_f32_e32 v100, v25
	v_sub_f32_e32 v25, v30, v176
	v_add_f32_e32 v24, v97, v24
	v_exp_f32_e32 v101, v25
	v_sub_f32_e32 v25, v69, v176
	v_add_f32_e32 v24, v98, v24
	v_exp_f32_e32 v85, v25
	v_sub_f32_e32 v25, v70, v176
	v_add_f32_e32 v24, v99, v24
	v_exp_f32_e32 v86, v25
	v_sub_f32_e32 v25, v71, v176
	v_add_f32_e32 v24, v100, v24
	v_exp_f32_e32 v87, v25
	v_sub_f32_e32 v25, v72, v176
	v_add_f32_e32 v24, v101, v24
	v_exp_f32_e32 v88, v25
	v_sub_f32_e32 v25, v73, v176
	v_add_f32_e32 v24, v85, v24
	v_exp_f32_e32 v89, v25
	v_sub_f32_e32 v25, v74, v176
	v_add_f32_e32 v24, v86, v24
	v_exp_f32_e32 v90, v25
	v_sub_f32_e32 v25, v75, v176
	v_add_f32_e32 v24, v87, v24
	v_exp_f32_e32 v91, v25
	v_sub_f32_e32 v25, v76, v176
	v_add_f32_e32 v24, v88, v24
	v_exp_f32_e32 v93, v25
	v_sub_f32_e32 v25, v77, v176
	v_add_f32_e32 v24, v89, v24
	v_exp_f32_e32 v77, v25
	v_sub_f32_e32 v25, v78, v176
	v_add_f32_e32 v24, v90, v24
	v_exp_f32_e32 v78, v25
	v_sub_f32_e32 v25, v79, v176
	v_add_f32_e32 v24, v91, v24
	v_exp_f32_e32 v79, v25
	v_sub_f32_e32 v25, v80, v176
	v_add_f32_e32 v24, v93, v24
	v_exp_f32_e32 v80, v25
	v_sub_f32_e32 v25, v81, v176
	v_add_f32_e32 v24, v77, v24
	v_exp_f32_e32 v81, v25
	v_sub_f32_e32 v25, v82, v176
	v_add_f32_e32 v24, v78, v24
	v_exp_f32_e32 v82, v25
	v_sub_f32_e32 v25, v83, v176
	v_add_f32_e32 v24, v79, v24
	v_exp_f32_e32 v83, v25
	v_sub_f32_e32 v25, v84, v176
	v_add_f32_e32 v24, v80, v24
	v_exp_f32_e32 v84, v25
	v_sub_f32_e32 v25, v182, v176
	v_add_f32_e32 v24, v81, v24
	v_exp_f32_e32 v69, v25
	v_sub_f32_e32 v25, v183, v176
	v_add_f32_e32 v24, v82, v24
	v_exp_f32_e32 v70, v25
	v_sub_f32_e32 v25, v184, v176
	v_add_f32_e32 v24, v83, v24
	v_exp_f32_e32 v71, v25
	v_sub_f32_e32 v25, v185, v176
	v_add_f32_e32 v24, v84, v24
	v_exp_f32_e32 v72, v25
	v_sub_f32_e32 v25, v186, v176
	v_add_f32_e32 v24, v69, v24
	v_exp_f32_e32 v73, v25
	v_sub_f32_e32 v25, v187, v176
	v_add_f32_e32 v24, v70, v24
	v_exp_f32_e32 v74, v25
	v_sub_f32_e32 v25, v173, v176
	v_add_f32_e32 v24, v71, v24
	v_exp_f32_e32 v75, v25
	v_sub_f32_e32 v25, v172, v176
	v_add_f32_e32 v24, v72, v24
	v_exp_f32_e32 v76, v25
	v_sub_f32_e32 v25, v175, v176
	v_add_f32_e32 v24, v73, v24
	v_exp_f32_e32 v25, v25
	v_sub_f32_e32 v26, v174, v176
	v_add_f32_e32 v24, v74, v24
	v_exp_f32_e32 v26, v26
	v_sub_f32_e32 v27, v177, v176
	v_add_f32_e32 v24, v75, v24
	v_exp_f32_e32 v27, v27
	v_sub_f32_e32 v28, v167, v176
	v_add_f32_e32 v24, v76, v24
	v_exp_f32_e32 v28, v28
	v_sub_f32_e32 v29, v168, v176
	v_add_f32_e32 v24, v25, v24
	v_exp_f32_e32 v29, v29
	v_sub_f32_e32 v30, v169, v176
	v_add_f32_e32 v24, v26, v24
	v_exp_f32_e32 v30, v30
	v_sub_f32_e32 v31, v170, v176
	v_add_f32_e32 v24, v27, v24
	v_exp_f32_e32 v31, v31
	v_add_f32_e32 v24, v28, v24
	v_add_f32_e32 v24, v29, v24
	v_add_f32_e32 v24, v30, v24
	v_add_f32_e32 v24, v31, v24
	v_add_f32_e32 v24, v68, v24
	ds_bpermute_b32 v167, v140, v24
	v_add_f32_e32 v44, v44, v110
	v_add_f32_e32 v45, v45, v111
	v_add_f32_e32 v46, v46, v112
	v_add_f32_e32 v47, v47, v113
	s_waitcnt lgkmcnt(0)
	v_add_f32_e32 v24, v24, v167
	ds_bpermute_b32 v167, v141, v24
	v_add_f32_e32 v23, 0, v23
	v_add_f32_e32 v22, 0, v22
	v_add_f32_e32 v23, v48, v23
	v_add_f32_e32 v22, v49, v22
	s_waitcnt lgkmcnt(0)
	v_add_f32_e32 v24, v24, v167
	v_fma_f32 v167, v162, s6, -v176
	v_exp_f32_e32 v167, v167
	v_add_f32_e32 v21, 0, v21
	v_add_f32_e32 v20, 0, v20
	v_add_f32_e32 v21, v50, v21
	v_add_f32_e32 v24, v167, v24
	v_div_scale_f32 v167, s[0:1], v24, v24, 1.0
	v_rcp_f32_e32 v168, v167
	v_add_f32_e32 v20, v51, v20
	v_add_f32_e32 v103, v53, v115
	v_add_f32_e32 v104, v54, v116
	v_fma_f32 v169, -v167, v168, 1.0
	v_fmac_f32_e32 v168, v169, v168
	v_div_scale_f32 v169, vcc, 1.0, v24, 1.0
	v_mul_f32_e32 v170, v169, v168
	v_fma_f32 v171, -v167, v170, v169
	v_fmac_f32_e32 v170, v171, v168
	v_fma_f32 v167, -v167, v170, v169
	v_div_fmas_f32 v167, v167, v168, v170
	ds_read2_b32 v[168:169], v139 offset0:175 offset1:176
	ds_read2_b32 v[170:171], v139 offset0:173 offset1:174
	v_div_fixup_f32 v24, v167, v24, 1.0
	v_add_f32_e32 v105, v55, v117
	v_add_f32_e32 v106, v56, v118
	s_waitcnt lgkmcnt(1)
	v_add_f32_e32 v167, v92, v169
	v_add_f32_e32 v32, v32, v167
	v_add_f32_e32 v167, v92, v168
	s_waitcnt lgkmcnt(0)
	v_add_f32_e32 v168, v92, v171
	v_add_f32_e32 v33, v33, v167
	v_add_f32_e32 v34, v34, v168
	v_add_f32_e32 v168, v92, v170
	v_max3_f32 v167, v32, s7, v33
	v_add_f32_e32 v35, v35, v168
	v_max3_f32 v167, v167, v34, v35
	v_max3_f32 v102, v167, v36, v37
	v_max3_f32 v102, v102, v38, v39
	v_max3_f32 v102, v102, v40, v41
	v_max3_f32 v102, v102, v42, v43
	v_max3_f32 v102, v102, v44, v45
	v_max3_f32 v102, v102, v46, v47
	v_max3_f32 v48, v102, v23, v22
	v_max3_f32 v48, v48, v21, v20
	v_add_f32_e32 v102, v52, v114
	v_max3_f32 v48, v48, v102, v103
	v_max3_f32 v48, v48, v104, v105
	v_add_f32_e32 v107, v57, v119
	v_max3_f32 v48, v48, v106, v107
	v_add_f32_e32 v108, v58, v120
	v_add_f32_e32 v109, v59, v121
	v_max3_f32 v48, v48, v108, v109
	v_add_f32_e32 v110, v60, v122
	v_add_f32_e32 v111, v61, v123
	v_max3_f32 v48, v48, v110, v111
	v_add_f32_e32 v112, v62, v124
	v_add_f32_e32 v113, v63, v125
	v_max3_f32 v48, v48, v112, v113
	v_add_f32_e32 v114, v64, v126
	v_add_f32_e32 v65, v65, v127
	v_max3_f32 v48, v48, v114, v65
	v_add_f32_e32 v66, v66, v136
	v_add_f32_e32 v67, v67, v137
	v_max3_f32 v48, v48, v66, v67
	v_add_f32_e32 v16, v16, v163
	v_add_f32_e32 v115, v17, v164
	v_max3_f32 v17, v48, v16, v115
	v_add_f32_e32 v116, v18, v165
	v_add_f32_e32 v117, v19, v166
	v_max3_f32 v17, v17, v116, v117
	ds_bpermute_b32 v18, v140, v17
	v_cvt_pk_bf16_f32 v94, v94, v95
	v_cvt_pk_bf16_f32 v95, v96, v97
	v_cvt_pk_bf16_f32 v96, v98, v99
	v_cvt_pk_bf16_f32 v97, v100, v101
	s_waitcnt lgkmcnt(0)
	v_max_f32_e32 v18, v18, v18
	v_max_f32_e32 v17, v17, v18
	ds_bpermute_b32 v18, v141, v17
	s_waitcnt lgkmcnt(0)
	v_max3_f32 v118, v17, v18, v133
	v_sub_f32_e32 v17, v32, v118
	v_exp_f32_e32 v57, v17
	v_sub_f32_e32 v18, v33, v118
	v_exp_f32_e32 v58, v18
	v_sub_f32_e32 v18, v34, v118
	v_exp_f32_e32 v59, v18
	v_sub_f32_e32 v18, v35, v118
	v_exp_f32_e32 v60, v18
	v_sub_f32_e32 v18, v36, v118
	v_add_f32_e32 v17, 0, v57
	v_exp_f32_e32 v61, v18
	v_sub_f32_e32 v18, v37, v118
	v_add_f32_e32 v17, v58, v17
	v_exp_f32_e32 v62, v18
	v_sub_f32_e32 v18, v38, v118
	v_add_f32_e32 v17, v59, v17
	v_exp_f32_e32 v63, v18
	v_sub_f32_e32 v18, v39, v118
	v_add_f32_e32 v17, v60, v17
	v_exp_f32_e32 v64, v18
	v_sub_f32_e32 v18, v40, v118
	v_add_f32_e32 v17, v61, v17
	v_exp_f32_e32 v49, v18
	v_sub_f32_e32 v18, v41, v118
	v_add_f32_e32 v17, v62, v17
	v_exp_f32_e32 v50, v18
	v_sub_f32_e32 v18, v42, v118
	v_add_f32_e32 v17, v63, v17
	v_exp_f32_e32 v51, v18
	v_sub_f32_e32 v18, v43, v118
	v_add_f32_e32 v17, v64, v17
	v_exp_f32_e32 v52, v18
	v_sub_f32_e32 v18, v44, v118
	v_add_f32_e32 v17, v49, v17
	v_exp_f32_e32 v53, v18
	v_sub_f32_e32 v18, v45, v118
	v_add_f32_e32 v17, v50, v17
	v_exp_f32_e32 v54, v18
	v_sub_f32_e32 v18, v46, v118
	v_add_f32_e32 v17, v51, v17
	v_exp_f32_e32 v55, v18
	v_sub_f32_e32 v18, v47, v118
	v_add_f32_e32 v17, v52, v17
	v_exp_f32_e32 v56, v18
	v_sub_f32_e32 v18, v23, v118
	v_add_f32_e32 v17, v53, v17
	v_exp_f32_e32 v41, v18
	v_sub_f32_e32 v18, v22, v118
	v_add_f32_e32 v17, v54, v17
	v_exp_f32_e32 v42, v18
	v_sub_f32_e32 v18, v21, v118
	v_add_f32_e32 v17, v55, v17
	v_exp_f32_e32 v43, v18
	v_sub_f32_e32 v18, v20, v118
	v_add_f32_e32 v17, v56, v17
	v_exp_f32_e32 v44, v18
	v_sub_f32_e32 v18, v102, v118
	v_add_f32_e32 v17, v41, v17
	v_exp_f32_e32 v45, v18
	v_sub_f32_e32 v18, v103, v118
	v_add_f32_e32 v17, v42, v17
	v_exp_f32_e32 v46, v18
	v_sub_f32_e32 v18, v104, v118
	v_add_f32_e32 v17, v43, v17
	v_exp_f32_e32 v47, v18
	v_sub_f32_e32 v18, v105, v118
	v_add_f32_e32 v17, v44, v17
	v_exp_f32_e32 v48, v18
	v_sub_f32_e32 v18, v106, v118
	v_add_f32_e32 v17, v45, v17
	v_exp_f32_e32 v33, v18
	v_sub_f32_e32 v18, v107, v118
	v_add_f32_e32 v17, v46, v17
	v_exp_f32_e32 v34, v18
	v_sub_f32_e32 v18, v108, v118
	v_add_f32_e32 v17, v47, v17
	v_exp_f32_e32 v35, v18
	v_sub_f32_e32 v18, v109, v118
	v_add_f32_e32 v17, v48, v17
	v_exp_f32_e32 v36, v18
	v_sub_f32_e32 v18, v110, v118
	v_add_f32_e32 v17, v33, v17
	v_exp_f32_e32 v37, v18
	v_sub_f32_e32 v18, v111, v118
	v_add_f32_e32 v17, v34, v17
	v_exp_f32_e32 v38, v18
	v_sub_f32_e32 v18, v112, v118
	v_add_f32_e32 v17, v35, v17
	v_exp_f32_e32 v39, v18
	v_sub_f32_e32 v18, v113, v118
	v_add_f32_e32 v17, v36, v17
	v_exp_f32_e32 v40, v18
	v_add_f32_e32 v17, v37, v17
	v_add_f32_e32 v17, v38, v17
	v_add_f32_e32 v17, v39, v17
	v_add_f32_e32 v18, v40, v17
	v_sub_f32_e32 v17, v114, v118
	v_exp_f32_e32 v17, v17
	v_sub_f32_e32 v16, v16, v118
	v_sub_f32_e32 v23, v116, v118
	v_exp_f32_e32 v23, v23
	v_add_f32_e32 v19, v17, v18
	v_sub_f32_e32 v18, v65, v118
	v_exp_f32_e32 v18, v18
	v_sub_f32_e32 v32, v117, v118
	v_exp_f32_e32 v32, v32
	v_cvt_pk_bf16_f32 v58, v57, v58
	v_add_f32_e32 v20, v18, v19
	v_sub_f32_e32 v19, v66, v118
	v_exp_f32_e32 v19, v19
	v_cvt_pk_bf16_f32 v59, v59, v60
	v_cvt_pk_bf16_f32 v60, v61, v62
	v_cvt_pk_bf16_f32 v61, v63, v64
	ds_read_b128 v[110:113], v142 offset:53888
	v_add_f32_e32 v21, v19, v20
	v_sub_f32_e32 v20, v67, v118
	v_exp_f32_e32 v20, v20
	s_nop 0
	v_add_f32_e32 v22, v20, v21
	v_exp_f32_e32 v21, v16
	s_nop 0
	v_add_f32_e32 v16, v21, v22
	v_sub_f32_e32 v22, v115, v118
	v_exp_f32_e32 v22, v22
	s_nop 0
	v_add_f32_e32 v16, v22, v16
	v_add_f32_e32 v16, v23, v16
	v_add_f32_e32 v16, v32, v16
	ds_bpermute_b32 v65, v140, v16
	s_waitcnt lgkmcnt(0)
	v_add_f32_e32 v16, v16, v65
	ds_bpermute_b32 v65, v141, v16
	s_waitcnt lgkmcnt(0)
	v_add_f32_e32 v16, v16, v65
	v_fma_f32 v65, v162, s6, -v118
	v_exp_f32_e32 v65, v65
	ds_read_b128 v[118:121], v142 offset:62336
	v_mfma_f32_16x16x32_bf16 v[114:117], v[110:113], v[94:97], 0
	v_add_f32_e32 v16, v65, v16
	v_div_scale_f32 v65, s[0:1], v16, v16, 1.0
	v_rcp_f32_e32 v66, v65
	v_mfma_f32_16x16x32_bf16 v[110:113], v[110:113], v[58:61], 0
	v_fma_f32 v67, -v65, v66, 1.0
	v_fmac_f32_e32 v66, v67, v66
	v_div_scale_f32 v67, vcc, 1.0, v16, 1.0
	v_mul_f32_e32 v102, v67, v66
	v_fma_f32 v103, -v65, v102, v67
	v_fmac_f32_e32 v102, v103, v66
	v_fma_f32 v65, -v65, v102, v67
	v_div_fmas_f32 v65, v65, v66, v102
	v_div_fixup_f32 v16, v65, v16, 1.0
	ds_read_b128 v[62:65], v142 offset:36992
	ds_read_b128 v[102:105], v142 offset:45440
	v_cvt_pk_bf16_f32 v86, v85, v86
	v_cvt_pk_bf16_f32 v87, v87, v88
	v_cvt_pk_bf16_f32 v88, v89, v90
	v_cvt_pk_bf16_f32 v89, v91, v93
	v_cvt_pk_bf16_f32 v50, v49, v50
	v_cvt_pk_bf16_f32 v51, v51, v52
	v_cvt_pk_bf16_f32 v52, v53, v54
	v_cvt_pk_bf16_f32 v53, v55, v56
	ds_read_b128 v[54:57], v142 offset:37056
	s_waitcnt lgkmcnt(2)
	v_mfma_f32_16x16x32_bf16 v[98:101], v[62:65], v[94:97], 0
	v_mfma_f32_16x16x32_bf16 v[62:65], v[62:65], v[58:61], 0
	s_waitcnt lgkmcnt(0)
	v_mfma_f32_16x16x32_bf16 v[98:101], v[54:57], v[86:89], v[98:101]
	v_mfma_f32_16x16x32_bf16 v[54:57], v[54:57], v[50:53], v[62:65]
	s_nop 4
	ds_read_b128 v[62:65], v142 offset:45504
	v_mfma_f32_16x16x32_bf16 v[106:109], v[102:105], v[94:97], 0
	v_mfma_f32_16x16x32_bf16 v[102:105], v[102:105], v[58:61], 0
	s_waitcnt lgkmcnt(0)
	v_mfma_f32_16x16x32_bf16 v[106:109], v[62:65], v[86:89], v[106:109]
	v_mfma_f32_16x16x32_bf16 v[62:65], v[62:65], v[50:53], v[102:105]
	s_nop 4
	ds_read_b128 v[102:105], v142 offset:53952
	s_waitcnt lgkmcnt(0)
	v_mfma_f32_16x16x32_bf16 v[114:117], v[102:105], v[86:89], v[114:117]
	v_mfma_f32_16x16x32_bf16 v[102:105], v[102:105], v[50:53], v[110:113]
	s_nop 2
	ds_read_b128 v[110:113], v142 offset:62400
	v_mfma_f32_16x16x32_bf16 v[58:61], v[118:121], v[58:61], 0
	s_waitcnt lgkmcnt(0)
	v_mfma_f32_16x16x32_bf16 v[50:53], v[110:113], v[50:53], v[58:61]
	v_cvt_pk_bf16_f32 v58, v77, v78
	v_cvt_pk_bf16_f32 v59, v79, v80
	v_cvt_pk_bf16_f32 v60, v81, v82
	v_cvt_pk_bf16_f32 v61, v83, v84
	v_cvt_pk_bf16_f32 v42, v41, v42
	v_cvt_pk_bf16_f32 v43, v43, v44
	v_cvt_pk_bf16_f32 v44, v45, v46
	v_cvt_pk_bf16_f32 v45, v47, v48
	ds_read_b128 v[46:49], v142 offset:37120
	s_waitcnt lgkmcnt(0)
	s_nop 3
	v_mfma_f32_16x16x32_bf16 v[78:81], v[46:49], v[58:61], v[98:101]
	s_nop 2
	ds_read_b128 v[98:101], v142 offset:62464
	v_mfma_f32_16x16x32_bf16 v[46:49], v[46:49], v[42:45], v[54:57]
	s_nop 2
	ds_read_b128 v[54:57], v142 offset:45568
	s_waitcnt lgkmcnt(0)
	v_mfma_f32_16x16x32_bf16 v[82:85], v[54:57], v[58:61], v[106:109]
	v_mfma_f32_16x16x32_bf16 v[54:57], v[54:57], v[42:45], v[62:65]
	s_nop 2
	ds_read_b128 v[62:65], v142 offset:54016
	v_mfma_f32_16x16x32_bf16 v[94:97], v[118:121], v[94:97], 0
	v_mfma_f32_16x16x32_bf16 v[86:89], v[110:113], v[86:89], v[94:97]
	s_waitcnt lgkmcnt(0)
	v_mfma_f32_16x16x32_bf16 v[94:97], v[62:65], v[58:61], v[114:117]
	v_mfma_f32_16x16x32_bf16 v[62:65], v[62:65], v[42:45], v[102:105]
	v_mfma_f32_16x16x32_bf16 v[42:45], v[98:101], v[42:45], v[50:53]
	v_cvt_pk_bf16_f32 v50, v69, v70
	v_cvt_pk_bf16_f32 v51, v71, v72
	v_cvt_pk_bf16_f32 v52, v73, v74
	v_cvt_pk_bf16_f32 v53, v75, v76
	v_cvt_pk_bf16_f32 v34, v33, v34
	v_cvt_pk_bf16_f32 v35, v35, v36
	v_cvt_pk_bf16_f32 v36, v37, v38
	v_cvt_pk_bf16_f32 v37, v39, v40
	ds_read_b128 v[38:41], v142 offset:37184
	s_waitcnt lgkmcnt(0)
	v_mfma_f32_16x16x32_bf16 v[70:73], v[38:41], v[50:53], v[78:81]
	v_mfma_f32_16x16x32_bf16 v[38:41], v[38:41], v[34:37], v[46:49]
	s_nop 2
	ds_read_b128 v[46:49], v142 offset:45632
	s_waitcnt lgkmcnt(0)
	v_mfma_f32_16x16x32_bf16 v[74:77], v[46:49], v[50:53], v[82:85]
	v_mfma_f32_16x16x32_bf16 v[46:49], v[46:49], v[34:37], v[54:57]
	s_nop 2
	ds_read_b128 v[54:57], v142 offset:54080
	s_waitcnt lgkmcnt(0)
	v_mfma_f32_16x16x32_bf16 v[78:81], v[54:57], v[50:53], v[94:97]
	v_mfma_f32_16x16x32_bf16 v[54:57], v[54:57], v[34:37], v[62:65]
	s_nop 2
	ds_read_b128 v[62:65], v142 offset:62528
	v_cvt_pk_bf16_f32 v26, v25, v26
	v_cvt_pk_bf16_f32 v27, v27, v28
	v_cvt_pk_bf16_f32 v28, v29, v30
	v_cvt_pk_bf16_f32 v29, v31, v68
	v_cvt_pk_bf16_f32 v18, v17, v18
	v_cvt_pk_bf16_f32 v19, v19, v20
	v_cvt_pk_bf16_f32 v20, v21, v22
	v_cvt_pk_bf16_f32 v21, v23, v32
	ds_read_b128 v[30:33], v142 offset:37248
	s_waitcnt lgkmcnt(1)
	v_mfma_f32_16x16x32_bf16 v[34:37], v[62:65], v[34:37], v[42:45]
	v_or_b32_e32 v22, 64, v132
	v_ashrrev_i32_e32 v23, 31, v22
	v_lshlrev_b64 v[22:23], 12, v[22:23]
	s_waitcnt lgkmcnt(0)
	v_mfma_f32_16x16x32_bf16 v[42:45], v[30:33], v[26:29], v[70:73]
	v_lshl_add_u64 v[22:23], v[134:135], 0, v[22:23]
	s_nop 6
	v_mul_f32_e32 v17, v24, v42
	v_mfma_f32_16x16x32_bf16 v[30:33], v[30:33], v[18:21], v[38:41]
	v_mul_f32_e32 v25, v24, v43
	s_nop 1
	ds_read_b128 v[38:41], v142 offset:45696
	v_mfma_f32_16x16x32_bf16 v[58:61], v[98:101], v[58:61], v[86:89]
	v_mfma_f32_16x16x32_bf16 v[50:53], v[62:65], v[50:53], v[58:61]
	s_waitcnt lgkmcnt(0)
	v_mfma_f32_16x16x32_bf16 v[58:61], v[38:41], v[26:29], v[74:77]
	v_mfma_f32_16x16x32_bf16 v[38:41], v[38:41], v[18:21], v[46:49]
	s_nop 2
	ds_read_b128 v[46:49], v142 offset:54144
	s_waitcnt lgkmcnt(0)
	v_mfma_f32_16x16x32_bf16 v[62:65], v[46:49], v[26:29], v[78:81]
	v_mfma_f32_16x16x32_bf16 v[46:49], v[46:49], v[18:21], v[54:57]
	s_nop 2
	ds_read_b128 v[54:57], v142 offset:62592
	s_waitcnt lgkmcnt(0)
	v_mfma_f32_16x16x32_bf16 v[18:21], v[54:57], v[18:21], v[34:37]
	v_cvt_pk_bf16_f32 v34, v17, v25
	v_mul_f32_e32 v17, v24, v44
	v_mul_f32_e32 v25, v24, v45
	v_mfma_f32_16x16x32_bf16 v[26:29], v[54:57], v[26:29], v[50:53]
	v_cvt_pk_bf16_f32 v35, v17, v25
	v_mul_f32_e32 v17, v24, v58
	global_store_dwordx2 v[22:23], v[34:35], off
	v_mul_f32_e32 v25, v24, v59
	v_cvt_pk_bf16_f32 v34, v17, v25
	v_mul_f32_e32 v17, v24, v60
	v_mul_f32_e32 v25, v24, v61
	v_cvt_pk_bf16_f32 v35, v17, v25
	v_mul_f32_e32 v17, v24, v62
	global_store_dwordx2 v[22:23], v[34:35], off offset:32
	v_mul_f32_e32 v25, v24, v63
	v_cvt_pk_bf16_f32 v34, v17, v25
	v_mul_f32_e32 v17, v24, v64
	v_mul_f32_e32 v25, v24, v65
	v_cvt_pk_bf16_f32 v35, v17, v25
	v_mul_f32_e32 v17, v24, v26
	global_store_dwordx2 v[22:23], v[34:35], off offset:64
	v_mul_f32_e32 v25, v24, v27
	v_cvt_pk_bf16_f32 v26, v17, v25
	v_mul_f32_e32 v17, v24, v28
	v_mul_f32_e32 v24, v24, v29
	v_cvt_pk_bf16_f32 v27, v17, v24
	global_store_dwordx2 v[22:23], v[26:27], off offset:96
	v_or_b32_e32 v22, 0x50, v132
	v_ashrrev_i32_e32 v23, 31, v22
	v_lshlrev_b64 v[22:23], 12, v[22:23]
	v_mul_f32_e32 v17, v16, v30
	v_mul_f32_e32 v24, v16, v31
	v_lshl_add_u64 v[22:23], v[134:135], 0, v[22:23]
	v_cvt_pk_bf16_f32 v24, v17, v24
	v_mul_f32_e32 v17, v16, v32
	v_mul_f32_e32 v25, v16, v33
	v_cvt_pk_bf16_f32 v25, v17, v25
	global_store_dwordx2 v[22:23], v[24:25], off
	v_mul_f32_e32 v17, v16, v38
	v_mul_f32_e32 v24, v16, v39
	v_cvt_pk_bf16_f32 v24, v17, v24
	v_mul_f32_e32 v17, v16, v40
	v_mul_f32_e32 v25, v16, v41
	v_cvt_pk_bf16_f32 v25, v17, v25
	global_store_dwordx2 v[22:23], v[24:25], off offset:32
	v_mul_f32_e32 v17, v16, v46
	v_mul_f32_e32 v24, v16, v47
	v_cvt_pk_bf16_f32 v24, v17, v24
	v_mul_f32_e32 v17, v16, v48
	v_mul_f32_e32 v25, v16, v49
	v_cvt_pk_bf16_f32 v25, v17, v25
	v_mul_f32_e32 v17, v16, v18
	v_mul_f32_e32 v18, v16, v19
	global_store_dwordx2 v[22:23], v[24:25], off offset:64
	v_cvt_pk_bf16_f32 v18, v17, v18
	v_mul_f32_e32 v17, v16, v20
	v_mul_f32_e32 v16, v16, v21
	v_cvt_pk_bf16_f32 v19, v17, v16
	global_store_dwordx2 v[22:23], v[18:19], off offset:96
	ds_read_b128 v[16:19], v153 offset:13824
	ds_read_b128 v[20:23], v153 offset:13888
	s_waitcnt vmcnt(27) lgkmcnt(1)
	v_mfma_f32_16x16x32_bf16 v[24:27], v[16:19], v[4:7], 0
	s_waitcnt vmcnt(25)
	v_mfma_f32_16x16x32_bf16 v[16:19], v[16:19], v[8:11], 0
	s_waitcnt lgkmcnt(0)
	v_mfma_f32_16x16x32_bf16 v[52:55], v[20:23], v[0:3], v[24:27]
	s_waitcnt vmcnt(24)
	v_mfma_f32_16x16x32_bf16 v[16:19], v[20:23], v[12:15], v[16:19]
	ds_read_b128 v[20:23], v153 offset:16128
	s_nop 0
	ds_read_b128 v[24:27], v153 offset:16192
	s_waitcnt lgkmcnt(1)
	v_mfma_f32_16x16x32_bf16 v[28:31], v[20:23], v[4:7], 0
	v_mfma_f32_16x16x32_bf16 v[20:23], v[20:23], v[8:11], 0
	s_waitcnt lgkmcnt(0)
	v_mfma_f32_16x16x32_bf16 v[56:59], v[24:27], v[0:3], v[28:31]
	v_mfma_f32_16x16x32_bf16 v[20:23], v[24:27], v[12:15], v[20:23]
	ds_read_b128 v[24:27], v153 offset:18432
	s_nop 2
	ds_read_b128 v[28:31], v153 offset:18496
	s_waitcnt lgkmcnt(1)
	v_mfma_f32_16x16x32_bf16 v[32:35], v[24:27], v[4:7], 0
	v_mfma_f32_16x16x32_bf16 v[24:27], v[24:27], v[8:11], 0
	s_waitcnt lgkmcnt(0)
	v_mfma_f32_16x16x32_bf16 v[60:63], v[28:31], v[0:3], v[32:35]
	v_mfma_f32_16x16x32_bf16 v[24:27], v[28:31], v[12:15], v[24:27]
	ds_read_b128 v[28:31], v153 offset:20736
	s_nop 2
	ds_read_b128 v[32:35], v153 offset:20800
	s_waitcnt lgkmcnt(1)
	v_mfma_f32_16x16x32_bf16 v[36:39], v[28:31], v[4:7], 0
	v_mfma_f32_16x16x32_bf16 v[28:31], v[28:31], v[8:11], 0
	s_waitcnt lgkmcnt(0)
	v_mfma_f32_16x16x32_bf16 v[64:67], v[32:35], v[0:3], v[36:39]
	v_mfma_f32_16x16x32_bf16 v[28:31], v[32:35], v[12:15], v[28:31]
	ds_read_b128 v[32:35], v153 offset:23040
	s_nop 2
	ds_read_b128 v[36:39], v153 offset:23104
	s_waitcnt lgkmcnt(1)
	v_mfma_f32_16x16x32_bf16 v[40:43], v[32:35], v[4:7], 0
	v_mfma_f32_16x16x32_bf16 v[32:35], v[32:35], v[8:11], 0
	s_waitcnt lgkmcnt(0)
	v_mfma_f32_16x16x32_bf16 v[68:71], v[36:39], v[0:3], v[40:43]
	v_mfma_f32_16x16x32_bf16 v[32:35], v[36:39], v[12:15], v[32:35]
	ds_read_b128 v[36:39], v153 offset:25344
	s_nop 2
	ds_read_b128 v[40:43], v153 offset:25408
	s_waitcnt lgkmcnt(1)
	v_mfma_f32_16x16x32_bf16 v[44:47], v[36:39], v[4:7], 0
	v_mfma_f32_16x16x32_bf16 v[36:39], v[36:39], v[8:11], 0
	s_waitcnt lgkmcnt(0)
	v_mfma_f32_16x16x32_bf16 v[72:75], v[40:43], v[0:3], v[44:47]
	v_mfma_f32_16x16x32_bf16 v[36:39], v[40:43], v[12:15], v[36:39]
	ds_read_b128 v[40:43], v153 offset:27648
	s_nop 2
	ds_read_b128 v[44:47], v153 offset:27712
	s_waitcnt lgkmcnt(1)
	v_mfma_f32_16x16x32_bf16 v[48:51], v[40:43], v[4:7], 0
	v_mfma_f32_16x16x32_bf16 v[40:43], v[40:43], v[8:11], 0
	s_waitcnt lgkmcnt(0)
	v_mfma_f32_16x16x32_bf16 v[76:79], v[44:47], v[0:3], v[48:51]
	v_mfma_f32_16x16x32_bf16 v[40:43], v[44:47], v[12:15], v[40:43]
	ds_read_b128 v[44:47], v153 offset:29952
	s_nop 2
	ds_read_b128 v[48:51], v153 offset:30016
	s_waitcnt lgkmcnt(1)
	v_mfma_f32_16x16x32_bf16 v[80:83], v[44:47], v[4:7], 0
	v_mfma_f32_16x16x32_bf16 v[44:47], v[44:47], v[8:11], 0
	s_waitcnt lgkmcnt(0)
	v_mfma_f32_16x16x32_bf16 v[80:83], v[48:51], v[0:3], v[80:83]
	v_mfma_f32_16x16x32_bf16 v[44:47], v[48:51], v[12:15], v[44:47]
	ds_read_b128 v[48:51], v153 offset:32256
	ds_read_b128 v[84:87], v153 offset:32320
	s_waitcnt lgkmcnt(1)
	v_mfma_f32_16x16x32_bf16 v[88:91], v[48:51], v[4:7], 0
	v_mfma_f32_16x16x32_bf16 v[48:51], v[48:51], v[8:11], 0
	s_waitcnt lgkmcnt(0)
	v_mfma_f32_16x16x32_bf16 v[116:119], v[84:87], v[0:3], v[88:91]
	v_mfma_f32_16x16x32_bf16 v[48:51], v[84:87], v[12:15], v[48:51]
	ds_read_b128 v[84:87], v153 offset:34560
	s_nop 2
	ds_read_b128 v[88:91], v153 offset:34624
	s_waitcnt lgkmcnt(1)
	v_mfma_f32_16x16x32_bf16 v[4:7], v[84:87], v[4:7], 0
	s_waitcnt lgkmcnt(0)
	v_mfma_f32_16x16x32_bf16 v[120:123], v[88:91], v[0:3], v[4:7]
	v_mfma_f32_16x16x32_bf16 v[0:3], v[84:87], v[8:11], 0
	v_mfma_f32_16x16x32_bf16 v[0:3], v[88:91], v[12:15], v[0:3]
	ds_read2_b32 v[8:9], v139 offset0:159 offset1:160
	ds_read2_b32 v[10:11], v139 offset0:157 offset1:158
	s_nop 1
	ds_read2_b32 v[6:7], v139 offset0:143 offset1:144
	ds_read2_b32 v[4:5], v139 offset0:141 offset1:142
	ds_read2_b32 v[12:13], v139 offset0:127 offset1:128
	ds_read2_b32 v[14:15], v139 offset0:125 offset1:126
	ds_read2_b32 v[96:97], v139 offset0:111 offset1:112
	ds_read2_b32 v[98:99], v139 offset0:109 offset1:110
	ds_read2_b32 v[100:101], v139 offset0:95 offset1:96
	ds_read2_b32 v[102:103], v139 offset0:93 offset1:94
	ds_read2_b32 v[104:105], v139 offset0:79 offset1:80
	ds_read2_b32 v[106:107], v139 offset0:77 offset1:78
	ds_read2_b32 v[108:109], v139 offset0:63 offset1:64
	ds_read2_b32 v[110:111], v139 offset0:61 offset1:62
	ds_read2_b32 v[112:113], v139 offset0:47 offset1:48
	ds_read2_b32 v[114:115], v139 offset0:45 offset1:46
	ds_read2_b32 v[124:125], v139 offset0:31 offset1:32
	ds_read2_b32 v[126:127], v139 offset0:29 offset1:30
	ds_read2_b32 v[136:137], v139 offset0:15 offset1:16
	ds_read2_b32 v[164:165], v139 offset0:13 offset1:14
	s_waitcnt lgkmcnt(14)
	v_add_f32_e32 v85, v92, v9
	v_add_f32_e32 v86, v92, v8
	v_add_f32_e32 v9, v52, v85
	v_add_f32_e32 v8, v53, v86
	v_add_f32_e32 v87, v92, v11
	v_add_f32_e32 v88, v92, v10
	v_max3_f32 v52, v9, s7, v8
	v_add_f32_e32 v11, v54, v87
	v_add_f32_e32 v10, v55, v88
	v_add_f32_e32 v53, v92, v7
	v_add_f32_e32 v54, v92, v6
	v_max3_f32 v52, v52, v11, v10
	v_add_f32_e32 v53, v56, v53
	v_add_f32_e32 v54, v57, v54
	v_add_f32_e32 v55, v92, v5
	v_add_f32_e32 v56, v92, v4
	v_max3_f32 v52, v52, v53, v54
	v_add_f32_e32 v55, v58, v55
	v_add_f32_e32 v56, v59, v56
	v_add_f32_e32 v89, 0, v13
	v_add_f32_e32 v90, 0, v12
	v_max3_f32 v52, v52, v55, v56
	v_add_f32_e32 v13, v60, v89
	v_add_f32_e32 v12, v61, v90
	v_add_f32_e32 v91, 0, v15
	v_add_f32_e32 v93, 0, v14
	v_max3_f32 v52, v52, v13, v12
	v_add_f32_e32 v15, v62, v91
	v_add_f32_e32 v14, v63, v93
	s_waitcnt lgkmcnt(13)
	v_add_f32_e32 v94, 0, v97
	v_add_f32_e32 v95, 0, v96
	v_max3_f32 v52, v52, v15, v14
	v_add_f32_e32 v57, v64, v94
	v_add_f32_e32 v58, v65, v95
	s_waitcnt lgkmcnt(12)
	v_add_f32_e32 v96, 0, v99
	v_add_f32_e32 v97, 0, v98
	v_max3_f32 v52, v52, v57, v58
	v_add_f32_e32 v59, v66, v96
	v_add_f32_e32 v60, v67, v97
	s_waitcnt lgkmcnt(11)
	v_add_f32_e32 v98, 0, v101
	v_add_f32_e32 v99, 0, v100
	v_max3_f32 v52, v52, v59, v60
	v_add_f32_e32 v61, v68, v98
	v_add_f32_e32 v62, v69, v99
	s_waitcnt lgkmcnt(10)
	v_add_f32_e32 v100, 0, v103
	v_add_f32_e32 v101, 0, v102
	v_max3_f32 v52, v52, v61, v62
	v_add_f32_e32 v63, v70, v100
	v_add_f32_e32 v64, v71, v101
	s_waitcnt lgkmcnt(9)
	v_add_f32_e32 v102, 0, v105
	v_add_f32_e32 v103, 0, v104
	v_max3_f32 v52, v52, v63, v64
	v_add_f32_e32 v65, v72, v102
	v_add_f32_e32 v66, v73, v103
	s_waitcnt lgkmcnt(8)
	v_add_f32_e32 v104, 0, v107
	v_add_f32_e32 v105, 0, v106
	v_max3_f32 v52, v52, v65, v66
	v_add_f32_e32 v67, v74, v104
	v_add_f32_e32 v68, v75, v105
	s_waitcnt lgkmcnt(7)
	v_add_f32_e32 v106, 0, v109
	v_add_f32_e32 v107, 0, v108
	v_max3_f32 v52, v52, v67, v68
	v_add_f32_e32 v163, v76, v106
	v_add_f32_e32 v166, v77, v107
	s_waitcnt lgkmcnt(6)
	v_add_f32_e32 v108, 0, v111
	v_add_f32_e32 v109, 0, v110
	v_max3_f32 v52, v52, v163, v166
	v_add_f32_e32 v167, v78, v108
	v_add_f32_e32 v168, v79, v109
	s_waitcnt lgkmcnt(5)
	v_add_f32_e32 v110, 0, v113
	v_add_f32_e32 v111, 0, v112
	v_max3_f32 v52, v52, v167, v168
	v_add_f32_e32 v169, v80, v110
	v_add_f32_e32 v170, v81, v111
	s_waitcnt lgkmcnt(4)
	v_add_f32_e32 v112, 0, v115
	v_add_f32_e32 v113, 0, v114
	v_max3_f32 v52, v52, v169, v170
	v_add_f32_e32 v171, v82, v112
	v_add_f32_e32 v172, v83, v113
	s_waitcnt lgkmcnt(3)
	v_add_f32_e32 v114, 0, v125
	v_add_f32_e32 v115, 0, v124
	s_waitcnt lgkmcnt(1)
	v_add_f32_e32 v69, 0, v137
	v_max3_f32 v52, v52, v171, v172
	v_add_f32_e32 v125, v116, v114
	v_add_f32_e32 v124, v117, v115
	v_add_f32_e32 v116, 0, v127
	v_add_f32_e32 v117, 0, v126
	v_add_f32_e32 v120, v120, v69
	v_add_f32_e32 v69, 0, v136
	v_max3_f32 v52, v52, v125, v124
	v_add_f32_e32 v118, v118, v116
	v_add_f32_e32 v119, v119, v117
	v_add_f32_e32 v121, v121, v69
	s_waitcnt lgkmcnt(0)
	v_add_f32_e32 v69, 0, v165
	v_max3_f32 v52, v52, v118, v119
	v_add_f32_e32 v122, v122, v69
	v_add_f32_e32 v69, 0, v164
	v_max3_f32 v52, v52, v120, v121
	v_add_f32_e32 v123, v123, v69
	v_max3_f32 v52, v52, v122, v123
	ds_bpermute_b32 v69, v140, v52
	v_add_f32_e32 v20, v20, v85
	v_add_f32_e32 v21, v21, v86
	v_add_f32_e32 v22, v22, v87
	v_add_f32_e32 v23, v23, v88
	s_waitcnt lgkmcnt(0)
	v_max_f32_e32 v69, v69, v69
	v_max_f32_e32 v52, v52, v69
	ds_bpermute_b32 v69, v141, v52
	v_add_f32_e32 v7, 0, v7
	v_add_f32_e32 v6, 0, v6
	v_add_f32_e32 v7, v24, v7
	v_add_f32_e32 v6, v25, v6
	s_waitcnt lgkmcnt(0)
	v_max3_f32 v126, v52, v69, v133
	v_sub_f32_e32 v9, v9, v126
	v_exp_f32_e32 v77, v9
	v_sub_f32_e32 v8, v8, v126
	v_exp_f32_e32 v78, v8
	v_sub_f32_e32 v52, v123, v126
	v_add_f32_e32 v9, 0, v77
	v_exp_f32_e32 v52, v52
	v_add_f32_e32 v8, v78, v9
	v_sub_f32_e32 v9, v11, v126
	v_exp_f32_e32 v79, v9
	v_sub_f32_e32 v9, v10, v126
	v_exp_f32_e32 v80, v9
	v_sub_f32_e32 v9, v53, v126
	v_exp_f32_e32 v81, v9
	v_sub_f32_e32 v9, v54, v126
	v_exp_f32_e32 v82, v9
	v_sub_f32_e32 v9, v55, v126
	v_add_f32_e32 v8, v79, v8
	v_exp_f32_e32 v83, v9
	v_sub_f32_e32 v9, v56, v126
	v_add_f32_e32 v8, v80, v8
	v_exp_f32_e32 v84, v9
	v_sub_f32_e32 v9, v13, v126
	v_add_f32_e32 v8, v81, v8
	v_exp_f32_e32 v69, v9
	v_sub_f32_e32 v9, v12, v126
	v_add_f32_e32 v8, v82, v8
	v_exp_f32_e32 v70, v9
	v_sub_f32_e32 v9, v15, v126
	v_add_f32_e32 v8, v83, v8
	v_exp_f32_e32 v71, v9
	v_sub_f32_e32 v9, v14, v126
	v_add_f32_e32 v8, v84, v8
	v_exp_f32_e32 v72, v9
	v_sub_f32_e32 v9, v57, v126
	v_add_f32_e32 v8, v69, v8
	v_exp_f32_e32 v73, v9
	v_sub_f32_e32 v9, v58, v126
	v_add_f32_e32 v8, v70, v8
	v_exp_f32_e32 v74, v9
	v_sub_f32_e32 v9, v59, v126
	v_add_f32_e32 v8, v71, v8
	v_exp_f32_e32 v75, v9
	v_sub_f32_e32 v9, v60, v126
	v_add_f32_e32 v8, v72, v8
	v_exp_f32_e32 v76, v9
	v_sub_f32_e32 v9, v61, v126
	v_add_f32_e32 v8, v73, v8
	v_exp_f32_e32 v61, v9
	v_sub_f32_e32 v9, v62, v126
	v_add_f32_e32 v8, v74, v8
	v_exp_f32_e32 v62, v9
	v_sub_f32_e32 v9, v63, v126
	v_add_f32_e32 v8, v75, v8
	v_exp_f32_e32 v63, v9
	v_sub_f32_e32 v9, v64, v126
	v_add_f32_e32 v8, v76, v8
	v_exp_f32_e32 v64, v9
	v_sub_f32_e32 v9, v65, v126
	v_add_f32_e32 v8, v61, v8
	v_exp_f32_e32 v65, v9
	v_sub_f32_e32 v9, v66, v126
	v_add_f32_e32 v8, v62, v8
	v_exp_f32_e32 v66, v9
	v_sub_f32_e32 v9, v67, v126
	v_add_f32_e32 v8, v63, v8
	v_exp_f32_e32 v67, v9
	v_sub_f32_e32 v9, v68, v126
	v_add_f32_e32 v8, v64, v8
	v_exp_f32_e32 v68, v9
	v_sub_f32_e32 v9, v163, v126
	v_add_f32_e32 v8, v65, v8
	v_exp_f32_e32 v53, v9
	v_sub_f32_e32 v9, v166, v126
	v_add_f32_e32 v8, v66, v8
	v_exp_f32_e32 v54, v9
	v_sub_f32_e32 v9, v167, v126
	v_add_f32_e32 v8, v67, v8
	v_exp_f32_e32 v55, v9
	v_sub_f32_e32 v9, v168, v126
	v_add_f32_e32 v8, v68, v8
	v_exp_f32_e32 v56, v9
	v_sub_f32_e32 v9, v169, v126
	v_add_f32_e32 v8, v53, v8
	v_exp_f32_e32 v57, v9
	v_sub_f32_e32 v9, v170, v126
	v_add_f32_e32 v8, v54, v8
	v_exp_f32_e32 v58, v9
	v_sub_f32_e32 v9, v171, v126
	v_add_f32_e32 v8, v55, v8
	v_exp_f32_e32 v59, v9
	v_sub_f32_e32 v9, v172, v126
	v_add_f32_e32 v8, v56, v8
	v_exp_f32_e32 v60, v9
	v_sub_f32_e32 v9, v125, v126
	v_add_f32_e32 v8, v57, v8
	v_exp_f32_e32 v9, v9
	v_sub_f32_e32 v10, v124, v126
	v_add_f32_e32 v8, v58, v8
	v_exp_f32_e32 v10, v10
	v_sub_f32_e32 v11, v118, v126
	v_add_f32_e32 v8, v59, v8
	v_exp_f32_e32 v11, v11
	v_sub_f32_e32 v12, v119, v126
	v_add_f32_e32 v8, v60, v8
	v_exp_f32_e32 v12, v12
	v_sub_f32_e32 v13, v120, v126
	v_add_f32_e32 v8, v9, v8
	v_exp_f32_e32 v13, v13
	v_sub_f32_e32 v14, v121, v126
	v_add_f32_e32 v8, v10, v8
	v_exp_f32_e32 v14, v14
	v_sub_f32_e32 v15, v122, v126
	v_add_f32_e32 v8, v11, v8
	v_exp_f32_e32 v15, v15
	v_add_f32_e32 v8, v12, v8
	v_add_f32_e32 v8, v13, v8
	v_add_f32_e32 v8, v14, v8
	v_add_f32_e32 v8, v15, v8
	v_add_f32_e32 v8, v52, v8
	ds_bpermute_b32 v118, v140, v8
	v_add_f32_e32 v5, 0, v5
	v_add_f32_e32 v4, 0, v4
	v_add_f32_e32 v5, v26, v5
	v_add_f32_e32 v4, v27, v4
	s_waitcnt lgkmcnt(0)
	v_add_f32_e32 v8, v8, v118
	ds_bpermute_b32 v118, v141, v8
	v_add_f32_e32 v25, v28, v89
	v_add_f32_e32 v26, v29, v90
	v_add_f32_e32 v27, v30, v91
	v_add_f32_e32 v28, v31, v93
	s_waitcnt lgkmcnt(0)
	v_add_f32_e32 v8, v8, v118
	v_fma_f32 v118, v162, s6, -v126
	v_exp_f32_e32 v118, v118
	v_add_f32_e32 v29, v32, v94
	v_add_f32_e32 v30, v33, v95
	v_add_f32_e32 v31, v34, v96
	v_add_f32_e32 v8, v118, v8
	v_div_scale_f32 v118, s[0:1], v8, v8, 1.0
	v_rcp_f32_e32 v119, v118
	v_add_f32_e32 v32, v35, v97
	v_add_f32_e32 v86, v37, v99
	v_add_f32_e32 v87, v38, v100
	v_fma_f32 v120, -v118, v119, 1.0
	v_fmac_f32_e32 v119, v120, v119
	v_div_scale_f32 v120, vcc, 1.0, v8, 1.0
	v_mul_f32_e32 v121, v120, v119
	v_fma_f32 v122, -v118, v121, v120
	v_fmac_f32_e32 v121, v122, v119
	v_fma_f32 v118, -v118, v121, v120
	v_div_fmas_f32 v118, v118, v119, v121
	v_div_fixup_f32 v8, v118, v8, 1.0
	ds_read2_b32 v[118:119], v139 offset0:175 offset1:176
	ds_read2_b32 v[120:121], v139 offset0:173 offset1:174
	v_add_f32_e32 v88, v39, v101
	v_add_f32_e32 v89, v40, v102
	v_add_f32_e32 v90, v41, v103
	s_waitcnt lgkmcnt(1)
	v_add_f32_e32 v119, v92, v119
	v_add_f32_e32 v118, v92, v118
	v_add_f32_e32 v16, v16, v119
	v_add_f32_e32 v17, v17, v118
	s_waitcnt lgkmcnt(0)
	v_add_f32_e32 v119, v92, v121
	v_add_f32_e32 v92, v92, v120
	v_max3_f32 v118, v16, s7, v17
	v_add_f32_e32 v18, v18, v119
	v_add_f32_e32 v19, v19, v92
	v_max3_f32 v92, v118, v18, v19
	v_max3_f32 v85, v92, v20, v21
	v_max3_f32 v85, v85, v22, v23
	v_max3_f32 v24, v85, v7, v6
	v_max3_f32 v24, v24, v5, v4
	v_max3_f32 v24, v24, v25, v26
	v_max3_f32 v24, v24, v27, v28
	v_max3_f32 v24, v24, v29, v30
	v_max3_f32 v24, v24, v31, v32
	v_add_f32_e32 v85, v36, v98
	v_max3_f32 v24, v24, v85, v86
	v_max3_f32 v24, v24, v87, v88
	v_max3_f32 v24, v24, v89, v90
	v_add_f32_e32 v91, v42, v104
	v_add_f32_e32 v92, v43, v105
	v_max3_f32 v24, v24, v91, v92
	v_add_f32_e32 v93, v44, v106
	v_add_f32_e32 v94, v45, v107
	v_max3_f32 v24, v24, v93, v94
	v_add_f32_e32 v95, v46, v108
	v_add_f32_e32 v96, v47, v109
	v_max3_f32 v24, v24, v95, v96
	v_add_f32_e32 v97, v48, v110
	v_add_f32_e32 v49, v49, v111
	v_max3_f32 v24, v24, v97, v49
	v_add_f32_e32 v50, v50, v112
	v_add_f32_e32 v51, v51, v113
	v_max3_f32 v24, v24, v50, v51
	v_add_f32_e32 v0, v0, v114
	v_add_f32_e32 v98, v1, v115
	v_max3_f32 v1, v24, v0, v98
	v_add_f32_e32 v99, v2, v116
	v_add_f32_e32 v100, v3, v117
	v_max3_f32 v1, v1, v99, v100
	ds_bpermute_b32 v2, v140, v1
	v_cvt_pk_bf16_f32 v78, v77, v78
	v_cvt_pk_bf16_f32 v79, v79, v80
	v_cvt_pk_bf16_f32 v80, v81, v82
	v_cvt_pk_bf16_f32 v81, v83, v84
	s_waitcnt lgkmcnt(0)
	v_max_f32_e32 v2, v2, v2
	v_max_f32_e32 v1, v1, v2
	ds_bpermute_b32 v2, v141, v1
	s_waitcnt lgkmcnt(0)
	v_max3_f32 v101, v1, v2, v133
	v_sub_f32_e32 v1, v16, v101
	v_exp_f32_e32 v41, v1
	v_sub_f32_e32 v2, v17, v101
	v_exp_f32_e32 v42, v2
	v_sub_f32_e32 v2, v18, v101
	v_exp_f32_e32 v43, v2
	v_sub_f32_e32 v2, v19, v101
	v_exp_f32_e32 v44, v2
	v_sub_f32_e32 v2, v20, v101
	v_add_f32_e32 v1, 0, v41
	v_exp_f32_e32 v45, v2
	v_sub_f32_e32 v2, v21, v101
	v_add_f32_e32 v1, v42, v1
	v_exp_f32_e32 v46, v2
	v_sub_f32_e32 v2, v22, v101
	v_add_f32_e32 v1, v43, v1
	v_exp_f32_e32 v47, v2
	v_sub_f32_e32 v2, v23, v101
	v_add_f32_e32 v1, v44, v1
	v_exp_f32_e32 v48, v2
	v_sub_f32_e32 v2, v7, v101
	v_add_f32_e32 v1, v45, v1
	v_exp_f32_e32 v33, v2
	v_sub_f32_e32 v2, v6, v101
	v_add_f32_e32 v1, v46, v1
	v_exp_f32_e32 v34, v2
	v_sub_f32_e32 v2, v5, v101
	v_add_f32_e32 v1, v47, v1
	v_exp_f32_e32 v35, v2
	v_sub_f32_e32 v2, v4, v101
	v_add_f32_e32 v1, v48, v1
	v_exp_f32_e32 v36, v2
	v_sub_f32_e32 v2, v25, v101
	v_add_f32_e32 v1, v33, v1
	v_exp_f32_e32 v37, v2
	v_sub_f32_e32 v2, v26, v101
	v_add_f32_e32 v1, v34, v1
	v_exp_f32_e32 v38, v2
	v_sub_f32_e32 v2, v27, v101
	v_add_f32_e32 v1, v35, v1
	v_exp_f32_e32 v39, v2
	v_sub_f32_e32 v2, v28, v101
	v_add_f32_e32 v1, v36, v1
	v_exp_f32_e32 v40, v2
	v_sub_f32_e32 v2, v29, v101
	v_add_f32_e32 v1, v37, v1
	v_exp_f32_e32 v25, v2
	v_sub_f32_e32 v2, v30, v101
	v_add_f32_e32 v1, v38, v1
	v_exp_f32_e32 v26, v2
	v_sub_f32_e32 v2, v31, v101
	v_add_f32_e32 v1, v39, v1
	v_exp_f32_e32 v27, v2
	v_sub_f32_e32 v2, v32, v101
	v_add_f32_e32 v1, v40, v1
	v_exp_f32_e32 v28, v2
	v_sub_f32_e32 v2, v85, v101
	v_add_f32_e32 v1, v25, v1
	v_exp_f32_e32 v29, v2
	v_sub_f32_e32 v2, v86, v101
	v_add_f32_e32 v1, v26, v1
	v_exp_f32_e32 v30, v2
	v_sub_f32_e32 v2, v87, v101
	v_add_f32_e32 v1, v27, v1
	v_exp_f32_e32 v31, v2
	v_sub_f32_e32 v2, v88, v101
	v_add_f32_e32 v1, v28, v1
	v_exp_f32_e32 v32, v2
	v_sub_f32_e32 v2, v89, v101
	v_add_f32_e32 v1, v29, v1
	v_exp_f32_e32 v17, v2
	v_sub_f32_e32 v2, v90, v101
	v_add_f32_e32 v1, v30, v1
	v_exp_f32_e32 v18, v2
	v_sub_f32_e32 v2, v91, v101
	v_add_f32_e32 v1, v31, v1
	v_exp_f32_e32 v19, v2
	v_sub_f32_e32 v2, v92, v101
	v_add_f32_e32 v1, v32, v1
	v_exp_f32_e32 v20, v2
	v_sub_f32_e32 v2, v93, v101
	v_add_f32_e32 v1, v17, v1
	v_exp_f32_e32 v21, v2
	v_sub_f32_e32 v2, v94, v101
	v_add_f32_e32 v1, v18, v1
	v_exp_f32_e32 v22, v2
	v_sub_f32_e32 v2, v95, v101
	v_add_f32_e32 v1, v19, v1
	v_exp_f32_e32 v23, v2
	v_sub_f32_e32 v2, v96, v101
	v_add_f32_e32 v1, v20, v1
	v_exp_f32_e32 v24, v2
	v_add_f32_e32 v1, v21, v1
	v_add_f32_e32 v1, v22, v1
	v_add_f32_e32 v1, v23, v1
	v_add_f32_e32 v2, v24, v1
	v_sub_f32_e32 v1, v97, v101
	v_exp_f32_e32 v1, v1
	v_sub_f32_e32 v0, v0, v101
	v_sub_f32_e32 v7, v99, v101
	v_exp_f32_e32 v7, v7
	v_add_f32_e32 v3, v1, v2
	v_sub_f32_e32 v2, v49, v101
	v_exp_f32_e32 v2, v2
	v_sub_f32_e32 v16, v100, v101
	v_exp_f32_e32 v16, v16
	v_cvt_pk_bf16_f32 v42, v41, v42
	v_add_f32_e32 v4, v2, v3
	v_sub_f32_e32 v3, v50, v101
	v_exp_f32_e32 v3, v3
	v_cvt_pk_bf16_f32 v43, v43, v44
	v_cvt_pk_bf16_f32 v44, v45, v46
	v_cvt_pk_bf16_f32 v45, v47, v48
	ds_read_b128 v[94:97], v142 offset:53952
	ds_read_b128 v[102:105], v142 offset:62400
	v_add_f32_e32 v5, v3, v4
	v_sub_f32_e32 v4, v51, v101
	v_exp_f32_e32 v4, v4
	s_nop 0
	v_add_f32_e32 v6, v4, v5
	v_exp_f32_e32 v5, v0
	s_nop 0
	v_add_f32_e32 v0, v5, v6
	v_sub_f32_e32 v6, v98, v101
	v_exp_f32_e32 v6, v6
	s_nop 0
	v_add_f32_e32 v0, v6, v0
	v_add_f32_e32 v0, v7, v0
	v_add_f32_e32 v0, v16, v0
	ds_bpermute_b32 v49, v140, v0
	s_waitcnt lgkmcnt(0)
	v_add_f32_e32 v0, v0, v49
	ds_bpermute_b32 v49, v141, v0
	s_waitcnt lgkmcnt(0)
	v_add_f32_e32 v0, v0, v49
	v_fma_f32 v49, v162, s6, -v101
	v_exp_f32_e32 v49, v49
	v_mfma_f32_16x16x32_bf16 v[98:101], v[94:97], v[78:81], 0
	v_add_f32_e32 v0, v49, v0
	v_div_scale_f32 v49, s[0:1], v0, v0, 1.0
	v_rcp_f32_e32 v50, v49
	v_mfma_f32_16x16x32_bf16 v[94:97], v[94:97], v[42:45], 0
	v_readlane_b32 s0, v254, 34
	s_add_i32 s29, s29, s0
	v_fma_f32 v51, -v49, v50, 1.0
	v_fmac_f32_e32 v50, v51, v50
	v_div_scale_f32 v51, vcc, 1.0, v0, 1.0
	v_mul_f32_e32 v85, v51, v50
	v_fma_f32 v86, -v49, v85, v51
	v_fmac_f32_e32 v85, v86, v50
	v_fma_f32 v49, -v49, v85, v51
	v_div_fmas_f32 v49, v49, v50, v85
	v_div_fixup_f32 v0, v49, v0, 1.0
	ds_read_b128 v[46:49], v142 offset:37056
	ds_read_b128 v[86:89], v142 offset:45504
	v_cvt_pk_bf16_f32 v70, v69, v70
	v_cvt_pk_bf16_f32 v71, v71, v72
	v_cvt_pk_bf16_f32 v72, v73, v74
	v_cvt_pk_bf16_f32 v73, v75, v76
	v_cvt_pk_bf16_f32 v34, v33, v34
	v_cvt_pk_bf16_f32 v35, v35, v36
	v_cvt_pk_bf16_f32 v36, v37, v38
	v_cvt_pk_bf16_f32 v37, v39, v40
	ds_read_b128 v[38:41], v142 offset:37120
	s_waitcnt lgkmcnt(2)
	v_mfma_f32_16x16x32_bf16 v[82:85], v[46:49], v[78:81], 0
	s_cmpk_lt_i32 s29, 0x100
	s_cselect_b64 s[0:1], -1, 0
	s_cmp_lt_u32 s11, 0x3fffffff
	v_mfma_f32_16x16x32_bf16 v[46:49], v[46:49], v[42:45], 0
	s_cselect_b64 s[6:7], -1, 0
	s_and_b64 s[0:1], s[36:37], s[0:1]
	s_and_b64 s[0:1], s[0:1], s[6:7]
	s_waitcnt lgkmcnt(0)
	v_mfma_f32_16x16x32_bf16 v[74:77], v[38:41], v[70:73], v[82:85]
	v_readlane_b32 s6, v254, 31
	s_add_i32 s28, s28, s6
	s_andn2_b64 vcc, exec, s[0:1]
	v_mfma_f32_16x16x32_bf16 v[38:41], v[38:41], v[34:37], v[46:49]
	s_mov_b32 s11, s20
	s_nop 1
	ds_read_b128 v[46:49], v142 offset:45568
	v_mfma_f32_16x16x32_bf16 v[90:93], v[86:89], v[78:81], 0
	v_mfma_f32_16x16x32_bf16 v[86:89], v[86:89], v[42:45], 0
	s_waitcnt lgkmcnt(0)
	v_mfma_f32_16x16x32_bf16 v[82:85], v[46:49], v[70:73], v[90:93]
	v_mfma_f32_16x16x32_bf16 v[46:49], v[46:49], v[34:37], v[86:89]
	s_nop 4
	ds_read_b128 v[86:89], v142 offset:54016
	s_waitcnt lgkmcnt(0)
	v_mfma_f32_16x16x32_bf16 v[90:93], v[86:89], v[70:73], v[98:101]
	v_mfma_f32_16x16x32_bf16 v[86:89], v[86:89], v[34:37], v[94:97]
	s_nop 2
	ds_read_b128 v[94:97], v142 offset:62464
	v_mfma_f32_16x16x32_bf16 v[42:45], v[102:105], v[42:45], 0
	s_waitcnt lgkmcnt(0)
	v_mfma_f32_16x16x32_bf16 v[34:37], v[94:97], v[34:37], v[42:45]
	v_cvt_pk_bf16_f32 v42, v61, v62
	v_cvt_pk_bf16_f32 v43, v63, v64
	v_cvt_pk_bf16_f32 v44, v65, v66
	v_cvt_pk_bf16_f32 v45, v67, v68
	v_cvt_pk_bf16_f32 v26, v25, v26
	v_cvt_pk_bf16_f32 v27, v27, v28
	v_cvt_pk_bf16_f32 v28, v29, v30
	v_cvt_pk_bf16_f32 v29, v31, v32
	ds_read_b128 v[30:33], v142 offset:37184
	v_mfma_f32_16x16x32_bf16 v[78:81], v[102:105], v[78:81], 0
	v_mfma_f32_16x16x32_bf16 v[70:73], v[94:97], v[70:73], v[78:81]
	s_nop 6
	ds_read_b128 v[78:81], v142 offset:62528
	s_waitcnt lgkmcnt(1)
	v_mfma_f32_16x16x32_bf16 v[62:65], v[30:33], v[42:45], v[74:77]
	v_mfma_f32_16x16x32_bf16 v[30:33], v[30:33], v[26:29], v[38:41]
	s_nop 2
	ds_read_b128 v[38:41], v142 offset:45632
	s_waitcnt lgkmcnt(0)
	v_mfma_f32_16x16x32_bf16 v[66:69], v[38:41], v[42:45], v[82:85]
	v_mfma_f32_16x16x32_bf16 v[38:41], v[38:41], v[26:29], v[46:49]
	s_nop 2
	ds_read_b128 v[46:49], v142 offset:54080
	s_waitcnt lgkmcnt(0)
	v_mfma_f32_16x16x32_bf16 v[74:77], v[46:49], v[42:45], v[90:93]
	v_mfma_f32_16x16x32_bf16 v[46:49], v[46:49], v[26:29], v[86:89]
	v_mfma_f32_16x16x32_bf16 v[26:29], v[78:81], v[26:29], v[34:37]
	v_cvt_pk_bf16_f32 v34, v53, v54
	v_cvt_pk_bf16_f32 v35, v55, v56
	v_cvt_pk_bf16_f32 v36, v57, v58
	v_cvt_pk_bf16_f32 v37, v59, v60
	v_cvt_pk_bf16_f32 v18, v17, v18
	v_cvt_pk_bf16_f32 v19, v19, v20
	v_cvt_pk_bf16_f32 v20, v21, v22
	v_cvt_pk_bf16_f32 v21, v23, v24
	ds_read_b128 v[22:25], v142 offset:37248
	s_waitcnt lgkmcnt(0)
	v_mfma_f32_16x16x32_bf16 v[54:57], v[22:25], v[34:37], v[62:65]
	v_mfma_f32_16x16x32_bf16 v[22:25], v[22:25], v[18:21], v[30:33]
	s_nop 2
	ds_read_b128 v[30:33], v142 offset:45696
	s_waitcnt lgkmcnt(0)
	v_mfma_f32_16x16x32_bf16 v[58:61], v[30:33], v[34:37], v[66:69]
	v_mfma_f32_16x16x32_bf16 v[30:33], v[30:33], v[18:21], v[38:41]
	s_nop 2
	ds_read_b128 v[38:41], v142 offset:54144
	s_waitcnt lgkmcnt(0)
	v_mfma_f32_16x16x32_bf16 v[62:65], v[38:41], v[34:37], v[74:77]
	v_mfma_f32_16x16x32_bf16 v[38:41], v[38:41], v[18:21], v[46:49]
	s_nop 2
	ds_read_b128 v[46:49], v142 offset:62592
	v_cvt_pk_bf16_f32 v10, v9, v10
	v_cvt_pk_bf16_f32 v11, v11, v12
	v_cvt_pk_bf16_f32 v12, v13, v14
	v_cvt_pk_bf16_f32 v13, v15, v52
	v_cvt_pk_bf16_f32 v2, v1, v2
	v_cvt_pk_bf16_f32 v3, v3, v4
	v_cvt_pk_bf16_f32 v4, v5, v6
	v_cvt_pk_bf16_f32 v5, v7, v16
	ds_read_b128 v[14:17], v142 offset:37312
	s_waitcnt lgkmcnt(1)
	v_mfma_f32_16x16x32_bf16 v[18:21], v[46:49], v[18:21], v[26:29]
	v_or_b32_e32 v6, 0x60, v132
	v_ashrrev_i32_e32 v7, 31, v6
	v_lshlrev_b64 v[6:7], 12, v[6:7]
	s_waitcnt lgkmcnt(0)
	v_mfma_f32_16x16x32_bf16 v[26:29], v[14:17], v[10:13], v[54:57]
	v_lshl_add_u64 v[6:7], v[134:135], 0, v[6:7]
	s_nop 6
	v_mul_f32_e32 v1, v8, v26
	v_mfma_f32_16x16x32_bf16 v[14:17], v[14:17], v[2:5], v[22:25]
	v_mul_f32_e32 v9, v8, v27
	s_nop 1
	ds_read_b128 v[22:25], v142 offset:45760
	v_mfma_f32_16x16x32_bf16 v[42:45], v[78:81], v[42:45], v[70:73]
	v_mfma_f32_16x16x32_bf16 v[34:37], v[46:49], v[34:37], v[42:45]
	s_waitcnt lgkmcnt(0)
	v_mfma_f32_16x16x32_bf16 v[42:45], v[22:25], v[10:13], v[58:61]
	v_mfma_f32_16x16x32_bf16 v[22:25], v[22:25], v[2:5], v[30:33]
	s_nop 2
	ds_read_b128 v[30:33], v142 offset:54208
	s_waitcnt lgkmcnt(0)
	v_mfma_f32_16x16x32_bf16 v[46:49], v[30:33], v[10:13], v[62:65]
	v_mfma_f32_16x16x32_bf16 v[30:33], v[30:33], v[2:5], v[38:41]
	s_nop 2
	ds_read_b128 v[38:41], v142 offset:62656
	s_waitcnt lgkmcnt(0)
	v_mfma_f32_16x16x32_bf16 v[2:5], v[38:41], v[2:5], v[18:21]
	v_cvt_pk_bf16_f32 v18, v1, v9
	v_mul_f32_e32 v1, v8, v28
	v_mul_f32_e32 v9, v8, v29
	v_mfma_f32_16x16x32_bf16 v[10:13], v[38:41], v[10:13], v[34:37]
	v_cvt_pk_bf16_f32 v19, v1, v9
	v_mul_f32_e32 v1, v8, v42
	global_store_dwordx2 v[6:7], v[18:19], off
	v_mul_f32_e32 v9, v8, v43
	v_cvt_pk_bf16_f32 v18, v1, v9
	v_mul_f32_e32 v1, v8, v44
	v_mul_f32_e32 v9, v8, v45
	v_cvt_pk_bf16_f32 v19, v1, v9
	v_mul_f32_e32 v1, v8, v46
	global_store_dwordx2 v[6:7], v[18:19], off offset:32
	v_mul_f32_e32 v9, v8, v47
	v_cvt_pk_bf16_f32 v18, v1, v9
	v_mul_f32_e32 v1, v8, v48
	v_mul_f32_e32 v9, v8, v49
	v_cvt_pk_bf16_f32 v19, v1, v9
	v_mul_f32_e32 v1, v8, v10
	global_store_dwordx2 v[6:7], v[18:19], off offset:64
	v_mul_f32_e32 v9, v8, v11
	v_cvt_pk_bf16_f32 v10, v1, v9
	v_mul_f32_e32 v1, v8, v12
	v_mul_f32_e32 v8, v8, v13
	v_cvt_pk_bf16_f32 v11, v1, v8
	global_store_dwordx2 v[6:7], v[10:11], off offset:96
	v_or_b32_e32 v6, 0x70, v132
	v_ashrrev_i32_e32 v7, 31, v6
	v_lshlrev_b64 v[6:7], 12, v[6:7]
	v_mul_f32_e32 v1, v0, v14
	v_mul_f32_e32 v8, v0, v15
	v_lshl_add_u64 v[6:7], v[134:135], 0, v[6:7]
	v_cvt_pk_bf16_f32 v8, v1, v8
	v_mul_f32_e32 v1, v0, v16
	v_mul_f32_e32 v9, v0, v17
	v_cvt_pk_bf16_f32 v9, v1, v9
	global_store_dwordx2 v[6:7], v[8:9], off
	v_mul_f32_e32 v1, v0, v22
	v_mul_f32_e32 v8, v0, v23
	v_cvt_pk_bf16_f32 v8, v1, v8
	v_mul_f32_e32 v1, v0, v24
	v_mul_f32_e32 v9, v0, v25
	v_cvt_pk_bf16_f32 v9, v1, v9
	global_store_dwordx2 v[6:7], v[8:9], off offset:32
	v_mul_f32_e32 v1, v0, v30
	v_mul_f32_e32 v8, v0, v31
	v_cvt_pk_bf16_f32 v8, v1, v8
	v_mul_f32_e32 v1, v0, v32
	v_mul_f32_e32 v9, v0, v33
	v_cvt_pk_bf16_f32 v9, v1, v9
	v_mul_f32_e32 v1, v0, v2
	v_mul_f32_e32 v2, v0, v3
	global_store_dwordx2 v[6:7], v[8:9], off offset:64
	v_cvt_pk_bf16_f32 v2, v1, v2
	v_mul_f32_e32 v1, v0, v4
	v_mul_f32_e32 v0, v0, v5
	v_cvt_pk_bf16_f32 v3, v1, v0
	global_store_dwordx2 v[6:7], v[2:3], off offset:96
	s_barrier
	s_cbranch_vccnz .LBB0_151
.LBB0_134:
	s_bfe_u32 s20, s29, 0x40002
	s_and_b32 s0, s28, 0xfffff800
	s_lshl_b32 s1, s20, 7
	s_or_b32 s21, s1, s0
	s_and_b32 s25, s29, 3
	s_add_i32 s36, s21, 0xffffff80
	s_cmp_lg_u32 s20, 0
	s_cselect_b64 s[0:1], -1, 0
	s_lshl_b32 s22, s25, 7
	v_lshl_add_u64 v[80:81], v[128:129], 0, s[22:23]
	s_or_b64 s[38:39], s[60:61], s[0:1]
	v_mov_b32_e32 v56, 0
	v_mov_b32_e32 v48, 0
	v_mov_b32_e32 v52, 0
	v_mov_b32_e32 v53, 0
	v_mov_b32_e32 v54, 0
	v_mov_b32_e32 v55, 0
	v_mov_b32_e32 v57, 0
	v_mov_b32_e32 v58, 0
	v_mov_b32_e32 v59, 0
	s_and_saveexec_b64 s[6:7], s[38:39]
	s_cbranch_execz .LBB0_136
	v_add_u32_e32 v50, s36, v143
	v_ashrrev_i32_e32 v51, 31, v50
	v_lshlrev_b64 v[50:51], 10, v[50:51]
	v_lshl_add_u64 v[50:51], v[80:81], 0, v[50:51]
	global_load_dwordx4 v[56:59], v[50:51], off
	global_load_dwordx4 v[52:55], v[50:51], off offset:512
.LBB0_136:
	s_or_b64 exec, exec, s[6:7]
	s_or_b64 s[38:39], s[0:1], s[62:63]
	v_mov_b32_e32 v60, 0
	v_mov_b32_e32 v61, 0
	v_mov_b32_e32 v62, 0
	v_mov_b32_e32 v63, 0
	v_mov_b32_e32 v64, 0
	v_mov_b32_e32 v65, 0
	v_mov_b32_e32 v66, 0
	v_mov_b32_e32 v67, 0
	s_and_saveexec_b64 s[6:7], s[38:39]
	s_cbranch_execz .LBB0_138
	v_add_u32_e32 v50, s36, v144
	v_ashrrev_i32_e32 v51, 31, v50
	v_lshlrev_b64 v[50:51], 10, v[50:51]
	v_lshl_add_u64 v[50:51], v[80:81], 0, v[50:51]
	global_load_dwordx4 v[64:67], v[50:51], off
	global_load_dwordx4 v[60:63], v[50:51], off offset:512
.LBB0_138:
	s_or_b64 exec, exec, s[6:7]
	s_or_b64 s[38:39], s[0:1], s[64:65]
	v_mov_b32_e32 v68, 0
	v_mov_b32_e32 v72, 0
	v_mov_b32_e32 v73, 0
	v_mov_b32_e32 v74, 0
	v_mov_b32_e32 v75, 0
	v_mov_b32_e32 v49, 0
	v_mov_b32_e32 v50, 0
	v_mov_b32_e32 v51, 0
	s_and_saveexec_b64 s[6:7], s[38:39]
	s_cbranch_execz .LBB0_140
	v_add_u32_e32 v48, s36, v145
	v_ashrrev_i32_e32 v49, 31, v48
	v_lshlrev_b64 v[48:49], 10, v[48:49]
	v_lshl_add_u64 v[70:71], v[80:81], 0, v[48:49]
	global_load_dwordx4 v[48:51], v[70:71], off
	global_load_dwordx4 v[72:75], v[70:71], off offset:512
.LBB0_140:
	s_or_b64 exec, exec, s[6:7]
	s_or_b64 s[6:7], s[0:1], s[66:67]
	v_mov_b32_e32 v69, 0
	v_mov_b32_e32 v70, 0
	v_mov_b32_e32 v71, 0
	v_mov_b32_e32 v76, 0
	v_mov_b32_e32 v77, 0
	v_mov_b32_e32 v78, 0
	v_mov_b32_e32 v79, 0
	s_and_saveexec_b64 s[0:1], s[6:7]
	s_cbranch_execz .LBB0_142
	v_add_u32_e32 v68, s36, v146
	v_ashrrev_i32_e32 v69, 31, v68
	v_lshlrev_b64 v[68:69], 10, v[68:69]
	v_lshl_add_u64 v[68:69], v[80:81], 0, v[68:69]
	global_load_dwordx4 v[76:79], v[68:69], off
	s_nop 0
	global_load_dwordx4 v[68:71], v[68:69], off offset:512
.LBB0_142:
	s_or_b64 exec, exec, s[0:1]
	s_lshl_b32 s6, s25, 3
	v_mov_b32_e32 v100, 0xf149f2ca
	v_mov_b32_e32 v101, 0xf149f2ca
	v_mov_b32_e32 v102, 0xf149f2ca
	s_and_saveexec_b64 s[0:1], s[8:9]
	v_add_u32_e32 v104, s6, v147
	v_ashrrev_i32_e32 v105, 31, v104
	v_lshl_add_u64 v[104:105], v[104:105], 2, s[4:5]
	global_load_dword v100, v[104:105], off
	s_or_b64 exec, exec, s[0:1]
	s_and_saveexec_b64 s[0:1], s[70:71]
	v_add_u32_e32 v104, s6, v149
	v_ashrrev_i32_e32 v105, 31, v104
	v_lshl_add_u64 v[104:105], v[104:105], 2, s[4:5]
	global_load_dword v101, v[104:105], off
	s_or_b64 exec, exec, s[0:1]
	s_and_saveexec_b64 s[0:1], s[72:73]
	v_add_u32_e32 v104, s6, v151
	v_ashrrev_i32_e32 v105, 31, v104
	v_lshl_add_u64 v[104:105], v[104:105], 2, s[4:5]
	global_load_dword v102, v[104:105], off
	s_or_b64 exec, exec, s[0:1]
	s_add_i32 s0, s6, s10
	s_ashr_i32 s1, s0, 31
	s_lshl_b64 s[6:7], s[0:1], 2
	s_add_u32 s6, s2, s6
	v_or_b32_e32 v132, s21, v138
	s_addc_u32 s7, s3, s7
	v_ashrrev_i32_e32 v133, 31, v132
	s_lshl_b32 s0, s0, 6
	v_lshlrev_b64 v[136:137], 12, v[132:133]
	s_ashr_i32 s1, s0, 31
	v_lshl_add_u64 v[0:1], s[26:27], 0, v[136:137]
	s_lshl_b64 s[0:1], s[0:1], 1
	v_lshl_add_u64 v[0:1], v[0:1], 0, s[0:1]
	global_load_dword v162, v205, s[6:7]
	v_lshl_add_u64 v[8:9], v[0:1], 0, v[204:205]
	s_mov_b32 s6, 0x10000
	v_add_co_u32_e32 v0, vcc, s6, v8
	global_load_dwordx4 v[84:87], v[8:9], off
	global_load_dwordx4 v[88:91], v[8:9], off offset:64
	v_addc_co_u32_e32 v1, vcc, 0, v9, vcc
	global_load_dwordx4 v[92:95], v[0:1], off
	global_load_dwordx4 v[96:99], v[0:1], off offset:64
	s_mov_b32 s6, 0x20000
	v_add_co_u32_e32 v0, vcc, s6, v8
	s_mov_b32 s6, 0x30000
	s_nop 0
	v_addc_co_u32_e32 v1, vcc, 0, v9, vcc
	global_load_dwordx4 v[36:39], v[0:1], off
	global_load_dwordx4 v[32:35], v[0:1], off offset:64
	v_add_co_u32_e32 v0, vcc, s6, v8
	s_mov_b32 s6, 0x40000
	s_nop 0
	v_addc_co_u32_e32 v1, vcc, 0, v9, vcc
	global_load_dwordx4 v[40:43], v[0:1], off
	global_load_dwordx4 v[44:47], v[0:1], off offset:64
	v_add_co_u32_e32 v0, vcc, s6, v8
	s_mov_b32 s6, 0x50000
	s_nop 0
	v_addc_co_u32_e32 v1, vcc, 0, v9, vcc
	global_load_dwordx4 v[20:23], v[0:1], off
	global_load_dwordx4 v[16:19], v[0:1], off offset:64
	v_add_co_u32_e32 v0, vcc, s6, v8
	s_mov_b32 s6, 0x60000
	s_nop 0
	v_addc_co_u32_e32 v1, vcc, 0, v9, vcc
	global_load_dwordx4 v[24:27], v[0:1], off
	global_load_dwordx4 v[28:31], v[0:1], off offset:64
	v_add_co_u32_e32 v0, vcc, s6, v8
	s_mov_b32 s6, 0x70000
	s_nop 0
	v_addc_co_u32_e32 v1, vcc, 0, v9, vcc
	v_add_co_u32_e32 v12, vcc, s6, v8
	global_load_dwordx4 v[4:7], v[0:1], off
	s_nop 0
	global_load_dwordx4 v[0:3], v[0:1], off offset:64
	v_addc_co_u32_e32 v13, vcc, 0, v9, vcc
	global_load_dwordx4 v[8:11], v[12:13], off
	s_nop 0
	global_load_dwordx4 v[12:15], v[12:13], off offset:64
	s_waitcnt vmcnt(17)
	ds_write_b128 v154, v[56:59]
	ds_write_b16 v155, v52 offset:36864
	ds_write_b16_d16_hi v155, v52 offset:37392
	ds_write_b16 v155, v53 offset:37920
	ds_write_b16_d16_hi v155, v53 offset:38448
	ds_write_b16 v155, v54 offset:38976
	ds_write_b16_d16_hi v155, v54 offset:39504
	ds_write_b16 v155, v55 offset:40032
	ds_write_b16_d16_hi v155, v55 offset:40560
	ds_write_b128 v156, v[64:67]
	ds_write_b16 v157, v60 offset:36864
	ds_write_b16_d16_hi v157, v60 offset:37392
	ds_write_b16 v157, v61 offset:37920
	ds_write_b16_d16_hi v157, v61 offset:38448
	ds_write_b16 v157, v62 offset:38976
	ds_write_b16_d16_hi v157, v62 offset:39504
	ds_write_b16 v157, v63 offset:40032
	ds_write_b16_d16_hi v157, v63 offset:40560
	ds_write_b128 v158, v[48:51]
	ds_write_b16 v159, v72 offset:36864
	ds_write_b16_d16_hi v159, v72 offset:37392
	ds_write_b16 v159, v73 offset:37920
	ds_write_b16_d16_hi v159, v73 offset:38448
	ds_write_b16 v159, v74 offset:38976
	ds_write_b16_d16_hi v159, v74 offset:39504
	ds_write_b16 v159, v75 offset:40032
	ds_write_b16_d16_hi v159, v75 offset:40560
	ds_write_b128 v160, v[76:79]
	ds_write_b16 v161, v68 offset:36864
	ds_write_b16_d16_hi v161, v68 offset:37392
	ds_write_b16 v161, v69 offset:37920
	ds_write_b16_d16_hi v161, v69 offset:38448
	ds_write_b16 v161, v70 offset:38976
	ds_write_b16_d16_hi v161, v70 offset:39504
	ds_write_b16 v161, v71 offset:40032
	ds_write_b16_d16_hi v161, v71 offset:40560
	v_mul_f32_e32 v103, 0x3fb8aa3b, v100
	v_mul_f32_e32 v104, 0x3fb8aa3b, v101
	v_mul_f32_e32 v105, 0x3fb8aa3b, v102
	v_cndmask_b32_e64 v100, v100, v103, s[8:9]
	v_cndmask_b32_e64 v101, v101, v104, s[70:71]
	v_cndmask_b32_e64 v102, v102, v105, s[72:73]
	ds_write_b32 v148, v100
	ds_write_b32 v150, v101
	ds_write_b32 v152, v102
	s_waitcnt lgkmcnt(0)
	s_barrier
	s_branch .Lattn_body
